# v8 + lazy softmax rescale: O/l rescaled only when running max grows by more than 8 (log2 units); mathematically identical softmax shift
# speedup vs baseline: 1.0125x; 1.0125x over previous
; #define LAS __attribute__((address_space(3)))
; template <int DK, bool IS_A>
; __device__ __forceinline__ void attn_unit(const Params& P, int l, LAS unsigned char* lds, int b, int grp, int qtok0, int nkeys) {
;     ...
;         for (int h = 0; h < 2; ++h) {
;             const LAS unsigned char* kb = lds + buf * A_BUF + kfo + h * 64 * AK_PITCH;
;             const LAS unsigned char* vb = lds + buf * A_BUF + vfo + h * 128;
;             f32x16 pa[2], pb[2];
; #pragma unroll
;             for (int jj = 0; jj < 2; ++jj)
; #pragma unroll
;                 for (int r = 0; r < 16; ++r) { pa[jj][r] = 0.f; pb[jj][r] = 0.f; }
;             __builtin_amdgcn_s_setprio(1);
; #pragma unroll
;             for (int i = 0; i < DK / 16; ++i)
; #pragma unroll
;                 for (int jj = 0; jj < 2; ++jj) {
;                     const bf16x8 kf = *(const LAS bf16x8*)(kb + jj * 32 * AK_PITCH + i * 32);
;                     pa[jj] = __builtin_amdgcn_mfma_f32_32x32x16_bf16(kf, qa[i], pa[jj], 0, 0, 0);
;                     pb[jj] = __builtin_amdgcn_mfma_f32_32x32x16_bf16(kf, qb[i], pb[jj], 0, 0, 0);
;                 }
;             __builtin_amdgcn_s_setprio(0);
.LBB0_366:
	s_bitcmp1_b32 s9, 0
	s_cselect_b32 s9, 0x8a00, 0
	s_add_i32 s9, s9, 0
	v_add_u32_e32 v64, s9, v178
	v_add_u32_e32 v195, v64, v194
	s_setprio 1
	ds_read_b128 v[64:67], v195
	ds_read_b128 v[204:207], v195 offset:32
	s_waitcnt lgkmcnt(1)
	v_mfma_f32_32x32x16_bf16 v[112:127], v[64:67], v[146:149], 0
	v_mfma_f32_32x32x16_bf16 v[96:111], v[64:67], v[150:153], 0
	ds_read_b128 v[64:67], v195 offset:4608
	s_waitcnt lgkmcnt(1)
	v_mfma_f32_32x32x16_bf16 v[112:127], v[204:207], v[154:157], v[112:127]
	v_mfma_f32_32x32x16_bf16 v[96:111], v[204:207], v[162:165], v[96:111]
	ds_read_b128 v[204:207], v195 offset:4640
	s_waitcnt lgkmcnt(1)
	v_mfma_f32_32x32x16_bf16 v[80:95], v[64:67], v[146:149], 0
	v_mfma_f32_32x32x16_bf16 v[64:79], v[64:67], v[150:153], 0
	s_waitcnt lgkmcnt(0)
	v_mfma_f32_32x32x16_bf16 v[80:95], v[204:207], v[154:157], v[80:95]
	v_mfma_f32_32x32x16_bf16 v[64:79], v[204:207], v[162:165], v[64:79]
	ds_read_b128 v[204:207], v195 offset:64
	s_waitcnt lgkmcnt(0)
	v_mfma_f32_32x32x16_bf16 v[112:127], v[204:207], v[158:161], v[112:127]
	v_mfma_f32_32x32x16_bf16 v[96:111], v[204:207], v[170:173], v[96:111]
	ds_read_b128 v[204:207], v195 offset:4672
	s_waitcnt lgkmcnt(0)
	v_mfma_f32_32x32x16_bf16 v[80:95], v[204:207], v[158:161], v[80:95]
	v_mfma_f32_32x32x16_bf16 v[64:79], v[204:207], v[170:173], v[64:79]
	ds_read_b128 v[204:207], v195 offset:96
	s_waitcnt lgkmcnt(0)
	v_mfma_f32_32x32x16_bf16 v[112:127], v[204:207], v[166:169], v[112:127]
	v_mfma_f32_32x32x16_bf16 v[96:111], v[204:207], v[174:177], v[96:111]
	ds_read_b128 v[204:207], v195 offset:4704
	s_waitcnt lgkmcnt(0)
	v_mfma_f32_32x32x16_bf16 v[80:95], v[204:207], v[166:169], v[80:95]
	v_mfma_f32_32x32x16_bf16 v[64:79], v[204:207], v[174:177], v[64:79]
	s_setprio 0
	s_nop 9
	v_max_f32_e32 v183, v80, v80
	v_max_f32_e32 v184, v112, v112
	v_max_f32_e32 v183, v184, v183
	v_max3_f32 v184, v81, v114, v82
	v_max3_f32 v183, v183, v113, v115
	v_max3_f32 v184, v184, v116, v84
	v_max3_f32 v183, v183, v83, v117
	v_max3_f32 v184, v184, v118, v86
	v_max3_f32 v183, v183, v85, v119
	v_max3_f32 v184, v184, v120, v88
	v_max3_f32 v183, v183, v87, v121
	v_max3_f32 v184, v184, v122, v90
	v_max3_f32 v183, v183, v89, v123
	v_max3_f32 v184, v184, v124, v92
	v_max3_f32 v183, v183, v91, v125
	v_max3_f32 v184, v184, v126, v94
	v_max3_f32 v183, v183, v93, v127
	v_max3_f32 v183, v183, v95, v184
	ds_bpermute_b32 v184, v179, v183
	s_waitcnt lgkmcnt(0)
	v_max3_f32 v204, v185, v183, v184
	v_add_f32_e32 v184, 0x41000000, v185
	v_cmp_gt_f32_e32 vcc, v204, v184
	s_cbranch_vccz .LBB0_368
	v_sub_f32_e32 v183, v185, v204
	v_exp_f32_e32 v184, v183
	s_nop 0
	v_pk_mul_f32 v[62:63], v[62:63], v[184:185] op_sel_hi:[1,0]
	v_pk_mul_f32 v[60:61], v[60:61], v[184:185] op_sel_hi:[1,0]
	v_pk_mul_f32 v[58:59], v[58:59], v[184:185] op_sel_hi:[1,0]
	v_pk_mul_f32 v[56:57], v[56:57], v[184:185] op_sel_hi:[1,0]
	v_pk_mul_f32 v[54:55], v[54:55], v[184:185] op_sel_hi:[1,0]
	v_pk_mul_f32 v[52:53], v[52:53], v[184:185] op_sel_hi:[1,0]
	v_pk_mul_f32 v[50:51], v[50:51], v[184:185] op_sel_hi:[1,0]
	v_pk_mul_f32 v[48:49], v[48:49], v[184:185] op_sel_hi:[1,0]
	v_pk_mul_f32 v[46:47], v[46:47], v[184:185] op_sel_hi:[1,0]
	v_pk_mul_f32 v[44:45], v[44:45], v[184:185] op_sel_hi:[1,0]
	v_pk_mul_f32 v[42:43], v[42:43], v[184:185] op_sel_hi:[1,0]
	v_pk_mul_f32 v[40:41], v[40:41], v[184:185] op_sel_hi:[1,0]
	v_pk_mul_f32 v[38:39], v[38:39], v[184:185] op_sel_hi:[1,0]
	v_pk_mul_f32 v[36:37], v[36:37], v[184:185] op_sel_hi:[1,0]
	v_pk_mul_f32 v[34:35], v[34:35], v[184:185] op_sel_hi:[1,0]
	v_pk_mul_f32 v[32:33], v[32:33], v[184:185] op_sel_hi:[1,0]
	v_mul_f32_e32 v191, v191, v184
	s_branch .LBB0_369

.LBB0_369:
	v_max_f32_e32 v183, v64, v64
	v_max_f32_e32 v184, v96, v96
	v_max_f32_e32 v183, v184, v183
	v_max3_f32 v184, v65, v98, v66
	v_max3_f32 v183, v183, v97, v99
	v_max3_f32 v184, v184, v100, v68
	v_max3_f32 v183, v183, v67, v101
	v_max3_f32 v184, v184, v102, v70
	v_max3_f32 v183, v183, v69, v103
	v_max3_f32 v184, v184, v104, v72
	v_max3_f32 v183, v183, v71, v105
	v_max3_f32 v184, v184, v106, v74
	v_max3_f32 v183, v183, v73, v107
	v_max3_f32 v184, v184, v108, v76
	v_max3_f32 v183, v183, v75, v109
	v_max3_f32 v184, v184, v110, v78
	v_max3_f32 v183, v183, v77, v111
	v_max3_f32 v183, v183, v79, v184
	ds_bpermute_b32 v184, v179, v183
	s_waitcnt lgkmcnt(0)
	v_max3_f32 v199, v187, v183, v184
	v_add_f32_e32 v184, 0x41000000, v187
	v_cmp_gt_f32_e32 vcc, v199, v184
	s_cbranch_vccz .LBB0_371
	v_sub_f32_e32 v183, v187, v199
	v_exp_f32_e32 v184, v183
	s_nop 0
	v_pk_mul_f32 v[30:31], v[30:31], v[184:185] op_sel_hi:[1,0]
	v_pk_mul_f32 v[28:29], v[28:29], v[184:185] op_sel_hi:[1,0]
	v_pk_mul_f32 v[26:27], v[26:27], v[184:185] op_sel_hi:[1,0]
	v_pk_mul_f32 v[24:25], v[24:25], v[184:185] op_sel_hi:[1,0]
	v_pk_mul_f32 v[22:23], v[22:23], v[184:185] op_sel_hi:[1,0]
	v_pk_mul_f32 v[20:21], v[20:21], v[184:185] op_sel_hi:[1,0]
	v_pk_mul_f32 v[18:19], v[18:19], v[184:185] op_sel_hi:[1,0]
	v_pk_mul_f32 v[16:17], v[16:17], v[184:185] op_sel_hi:[1,0]
	v_pk_mul_f32 v[14:15], v[14:15], v[184:185] op_sel_hi:[1,0]
	v_pk_mul_f32 v[12:13], v[12:13], v[184:185] op_sel_hi:[1,0]
	v_pk_mul_f32 v[10:11], v[10:11], v[184:185] op_sel_hi:[1,0]
	v_pk_mul_f32 v[8:9], v[8:9], v[184:185] op_sel_hi:[1,0]
	v_pk_mul_f32 v[6:7], v[6:7], v[184:185] op_sel_hi:[1,0]
	v_pk_mul_f32 v[4:5], v[4:5], v[184:185] op_sel_hi:[1,0]
	v_pk_mul_f32 v[2:3], v[2:3], v[184:185] op_sel_hi:[1,0]
	v_pk_mul_f32 v[0:1], v[0:1], v[184:185] op_sel_hi:[1,0]
	v_mul_f32_e32 v182, v182, v184
	s_branch .LBB0_372

; #define LAS __attribute__((address_space(3)))
; __device__ __forceinline__ unsigned pk2(float lo, float hi) { f32x2_t v = {lo, hi}; bf16x2_t b = __builtin_convertvector(v, bf16x2_t); return __builtin_bit_cast(unsigned, b); }
; template <int DK, bool IS_A>
; __device__ __forceinline__ void attn_unit(const Params& P, int l, LAS unsigned char* lds, int b, int grp, int qtok0, int nkeys) {
;     ...
;             AT_SOFTMAX(pa, ma, la, oa0, oa1);
;             AT_SOFTMAX(pb, mb, lb_, ob0, ob1);
;     ...
; #pragma unroll
;             for (int ks = 0; ks < 4; ++ks) {
;                 const int o8 = 8 * (ks & 1);
;                 u32x4 w; const f32x16& xa = pa[ks >> 1]; const f32x16& xb = pb[ks >> 1];
;                 w.x = pk2(xa[o8], xa[o8 + 1]); w.y = pk2(xa[o8 + 2], xa[o8 + 3]); w.z = pk2(xa[o8 + 4], xa[o8 + 5]); w.w = pk2(xa[o8 + 6], xa[o8 + 7]);
;                 const bf16x8 pfa = __builtin_bit_cast(bf16x8, w);
;                 w.x = pk2(xb[o8], xb[o8 + 1]); w.y = pk2(xb[o8 + 2], xb[o8 + 3]); w.z = pk2(xb[o8 + 4], xb[o8 + 5]); w.w = pk2(xb[o8 + 6], xb[o8 + 7]);
;                 const bf16x8 pfb = __builtin_bit_cast(bf16x8, w);
;                 const u32x2 a0 = *(const LAS u32x2*)(vb + ks * 32), a1 = *(const LAS u32x2*)(vb + ks * 32 + 16);
;                 const u32x2 c0 = *(const LAS u32x2*)(vb + 32 * AV_PITCH + ks * 32), c1 = *(const LAS u32x2*)(vb + 32 * AV_PITCH + ks * 32 + 16);
;                 const bf16x8 v0 = __builtin_bit_cast(bf16x8, ((u32x4){a0.x, a0.y, a1.x, a1.y})), v1 = __builtin_bit_cast(bf16x8, ((u32x4){c0.x, c0.y, c1.x, c1.y}));
;                 oa0 = __builtin_amdgcn_mfma_f32_32x32x16_bf16(v0, pfa, oa0, 0, 0, 0);
;                 oa1 = __builtin_amdgcn_mfma_f32_32x32x16_bf16(v1, pfa, oa1, 0, 0, 0);
;                 ob0 = __builtin_amdgcn_mfma_f32_32x32x16_bf16(v0, pfb, ob0, 0, 0, 0);
;                 ob1 = __builtin_amdgcn_mfma_f32_32x32x16_bf16(v1, pfb, ob1, 0, 0, 0);
;             }
.LBB0_372:
	v_sub_f32_e32 v112, v112, v204
	v_exp_f32_e32 v112, v112
	v_sub_f32_e32 v113, v113, v204
	v_exp_f32_e32 v113, v113
	v_sub_f32_e32 v114, v114, v204
	v_exp_f32_e32 v114, v114
	v_sub_f32_e32 v115, v115, v204
	v_exp_f32_e32 v115, v115
	v_sub_f32_e32 v116, v116, v204
	v_add_f32_e32 v183, 0, v112
	v_exp_f32_e32 v116, v116
	v_sub_f32_e32 v117, v117, v204
	v_add_f32_e32 v183, v113, v183
	v_exp_f32_e32 v117, v117
	v_sub_f32_e32 v118, v118, v204
	v_add_f32_e32 v183, v114, v183
	v_exp_f32_e32 v118, v118
	v_sub_f32_e32 v119, v119, v204
	v_add_f32_e32 v183, v115, v183
	v_exp_f32_e32 v119, v119
	v_sub_f32_e32 v120, v120, v204
	v_add_f32_e32 v183, v116, v183
	v_exp_f32_e32 v120, v120
	v_sub_f32_e32 v121, v121, v204
	v_add_f32_e32 v183, v117, v183
	v_exp_f32_e32 v121, v121
	v_sub_f32_e32 v122, v122, v204
	v_add_f32_e32 v183, v118, v183
	v_exp_f32_e32 v122, v122
	v_sub_f32_e32 v123, v123, v204
	v_add_f32_e32 v183, v119, v183
	v_exp_f32_e32 v123, v123
	v_sub_f32_e32 v124, v124, v204
	v_add_f32_e32 v183, v120, v183
	v_exp_f32_e32 v124, v124
	v_sub_f32_e32 v125, v125, v204
	v_add_f32_e32 v183, v121, v183
	v_exp_f32_e32 v125, v125
	v_sub_f32_e32 v126, v126, v204
	v_add_f32_e32 v183, v122, v183
	v_exp_f32_e32 v126, v126
	v_sub_f32_e32 v127, v127, v204
	v_add_f32_e32 v183, v123, v183
	v_exp_f32_e32 v127, v127
	v_sub_f32_e32 v80, v80, v204
	v_add_f32_e32 v183, v124, v183
	v_exp_f32_e32 v185, v80
	v_sub_f32_e32 v80, v81, v204
	v_add_f32_e32 v183, v125, v183
	v_exp_f32_e32 v223, v80
	v_sub_f32_e32 v81, v82, v204
	v_add_f32_e32 v80, v126, v183
	v_exp_f32_e32 v224, v81
	v_sub_f32_e32 v81, v83, v204
	v_add_f32_e32 v80, v127, v80
	v_exp_f32_e32 v225, v81
	v_sub_f32_e32 v81, v84, v204
	v_add_f32_e32 v80, v185, v80
	v_exp_f32_e32 v226, v81
	v_sub_f32_e32 v81, v85, v204
	v_add_f32_e32 v80, v223, v80
	v_exp_f32_e32 v227, v81
	v_sub_f32_e32 v81, v86, v204
	v_add_f32_e32 v80, v224, v80
	v_exp_f32_e32 v228, v81
	v_sub_f32_e32 v81, v87, v204
	v_add_f32_e32 v80, v225, v80
	v_exp_f32_e32 v229, v81
	v_sub_f32_e32 v81, v88, v204
	v_add_f32_e32 v80, v226, v80
	v_exp_f32_e32 v230, v81
	v_sub_f32_e32 v81, v89, v204
	v_add_f32_e32 v80, v227, v80
	v_exp_f32_e32 v232, v81
	v_add_f32_e32 v80, v228, v80
	v_add_f32_e32 v80, v229, v80
	v_add_f32_e32 v80, v230, v80
	v_add_f32_e32 v236, v232, v80
	v_sub_f32_e32 v80, v90, v204
	v_exp_f32_e32 v237, v80
	v_sub_f32_e32 v80, v91, v204
	v_exp_f32_e32 v238, v80
	v_sub_f32_e32 v80, v92, v204
	v_exp_f32_e32 v92, v80
	v_add_u32_e32 v80, s9, v180
	v_sub_f32_e32 v81, v96, v199
	v_add_u32_e32 v88, v80, v186
	v_exp_f32_e32 v187, v81
	v_sub_f32_e32 v81, v97, v199
	v_add_u32_e32 v183, 0x4800, v88
	v_add_u32_e32 v184, 0x6800, v88
	v_exp_f32_e32 v205, v81
	ds_read2_b64 v[80:83], v183 offset1:2
	ds_read2_b64 v[88:91], v184 offset0:32 offset1:34
	v_sub_f32_e32 v96, v99, v199
	v_sub_f32_e32 v84, v98, v199
	v_exp_f32_e32 v207, v96
	v_sub_f32_e32 v96, v100, v199
	v_exp_f32_e32 v206, v84
	v_cvt_pk_bf16_f32 v84, v112, v113
	v_cvt_pk_bf16_f32 v85, v114, v115
	v_cvt_pk_bf16_f32 v86, v116, v117
	v_cvt_pk_bf16_f32 v87, v118, v119
	v_exp_f32_e32 v208, v96
	v_sub_f32_e32 v96, v101, v199
	s_waitcnt lgkmcnt(1)
	v_mfma_f32_32x32x16_bf16 v[48:63], v[80:83], v[84:87], v[48:63]
	v_exp_f32_e32 v209, v96
	v_sub_f32_e32 v96, v102, v199
	v_exp_f32_e32 v210, v96
	v_sub_f32_e32 v96, v107, v199
	v_exp_f32_e32 v215, v96
	v_sub_f32_e32 v96, v108, v199
	v_exp_f32_e32 v216, v96
	s_waitcnt lgkmcnt(0)
	v_mfma_f32_32x32x16_bf16 v[32:47], v[88:91], v[84:87], v[32:47]
	v_sub_f32_e32 v84, v103, v199
	v_exp_f32_e32 v211, v84
	v_cvt_pk_bf16_f32 v84, v187, v205
	v_cvt_pk_bf16_f32 v85, v206, v207
	v_cvt_pk_bf16_f32 v86, v208, v209
	v_cvt_pk_bf16_f32 v87, v210, v211
	v_sub_f32_e32 v96, v109, v199
	v_exp_f32_e32 v217, v96
	v_mfma_f32_32x32x16_bf16 v[16:31], v[80:83], v[84:87], v[16:31]
	v_sub_f32_e32 v80, v93, v204
	v_exp_f32_e32 v93, v80
	v_sub_f32_e32 v80, v104, v199
	v_exp_f32_e32 v212, v80
	v_sub_f32_e32 v80, v105, v199
	v_exp_f32_e32 v213, v80
	ds_read2_b64 v[80:83], v183 offset0:4 offset1:6
	v_mfma_f32_32x32x16_bf16 v[0:15], v[88:91], v[84:87], v[0:15]
	ds_read2_b64 v[88:91], v184 offset0:36 offset1:38
	v_sub_f32_e32 v84, v106, v199
	v_exp_f32_e32 v214, v84
	v_cvt_pk_bf16_f32 v84, v120, v121
	v_cvt_pk_bf16_f32 v85, v122, v123
	v_cvt_pk_bf16_f32 v86, v124, v125
	v_cvt_pk_bf16_f32 v87, v126, v127
	v_sub_f32_e32 v96, v110, v199
	v_exp_f32_e32 v218, v96
	s_waitcnt lgkmcnt(1)
	v_mfma_f32_32x32x16_bf16 v[48:63], v[80:83], v[84:87], v[48:63]
	v_sub_f32_e32 v64, v64, v199
	v_exp_f32_e32 v220, v64
	v_sub_f32_e32 v64, v65, v199
	v_exp_f32_e32 v221, v64
	v_sub_f32_e32 v64, v66, v199
	v_exp_f32_e32 v222, v64
	v_sub_f32_e32 v64, v67, v199
	s_waitcnt lgkmcnt(0)
	v_mfma_f32_32x32x16_bf16 v[32:47], v[88:91], v[84:87], v[32:47]
	v_sub_f32_e32 v84, v111, v199
	v_exp_f32_e32 v219, v84
	v_cvt_pk_bf16_f32 v84, v212, v213
	v_cvt_pk_bf16_f32 v85, v214, v215
	v_cvt_pk_bf16_f32 v86, v216, v217
	v_cvt_pk_bf16_f32 v87, v218, v219
	s_nop 1
	v_mfma_f32_32x32x16_bf16 v[16:31], v[80:83], v[84:87], v[16:31]
	v_sub_f32_e32 v80, v94, v204
	v_exp_f32_e32 v94, v80
	ds_read2_b64 v[80:83], v183 offset0:8 offset1:10
	v_mfma_f32_32x32x16_bf16 v[0:15], v[88:91], v[84:87], v[0:15]
	ds_read2_b64 v[88:91], v184 offset0:40 offset1:42
	v_cvt_pk_bf16_f32 v84, v185, v223
	v_exp_f32_e32 v223, v64
	v_sub_f32_e32 v64, v68, v199
	v_cvt_pk_bf16_f32 v85, v224, v225
	v_exp_f32_e32 v224, v64
	v_sub_f32_e32 v64, v69, v199
	v_exp_f32_e32 v225, v64
	v_sub_f32_e32 v64, v70, v199
	v_cvt_pk_bf16_f32 v86, v226, v227
	v_exp_f32_e32 v226, v64
	v_sub_f32_e32 v64, v71, v199
	v_exp_f32_e32 v227, v64
	v_cvt_pk_bf16_f32 v87, v228, v229
	v_sub_f32_e32 v68, v95, v204
	v_cvt_pk_bf16_f32 v64, v220, v221
	s_waitcnt lgkmcnt(1)
; #define LAS __attribute__((address_space(3)))
; template <int DK, bool IS_A>
; __device__ __forceinline__ void attn_unit(const Params& P, int l, LAS unsigned char* lds, int b, int grp, int qtok0, int nkeys) {
;     ...
;             __builtin_amdgcn_s_setprio(1);
; #pragma unroll
;             for (int i = 0; i < DK / 16; ++i)
; #pragma unroll
;                 for (int jj = 0; jj < 2; ++jj) {
;                     const bf16x8 kf = *(const LAS bf16x8*)(kb + jj * 32 * AK_PITCH + i * 32);
;                     pa[jj] = __builtin_amdgcn_mfma_f32_32x32x16_bf16(kf, qa[i], pa[jj], 0, 0, 0);
;                     pb[jj] = __builtin_amdgcn_mfma_f32_32x32x16_bf16(kf, qb[i], pb[jj], 0, 0, 0);
;                 }
;             __builtin_amdgcn_s_setprio(0);
;     ...
;             AT_SOFTMAX(pa, ma, la, oa0, oa1);
;             AT_SOFTMAX(pb, mb, lb_, ob0, ob1);
;     ...
; #pragma unroll
;             for (int ks = 0; ks < 4; ++ks) {
;                 const int o8 = 8 * (ks & 1);
;                 u32x4 w; const f32x16& xa = pa[ks >> 1]; const f32x16& xb = pb[ks >> 1];
;                 w.x = pk2(xa[o8], xa[o8 + 1]); w.y = pk2(xa[o8 + 2], xa[o8 + 3]); w.z = pk2(xa[o8 + 4], xa[o8 + 5]); w.w = pk2(xa[o8 + 6], xa[o8 + 7]);
;                 const bf16x8 pfa = __builtin_bit_cast(bf16x8, w);
;                 w.x = pk2(xb[o8], xb[o8 + 1]); w.y = pk2(xb[o8 + 2], xb[o8 + 3]); w.z = pk2(xb[o8 + 4], xb[o8 + 5]); w.w = pk2(xb[o8 + 6], xb[o8 + 7]);
;                 const bf16x8 pfb = __builtin_bit_cast(bf16x8, w);
;                 const u32x2 a0 = *(const LAS u32x2*)(vb + ks * 32), a1 = *(const LAS u32x2*)(vb + ks * 32 + 16);
;                 const u32x2 c0 = *(const LAS u32x2*)(vb + 32 * AV_PITCH + ks * 32), c1 = *(const LAS u32x2*)(vb + 32 * AV_PITCH + ks * 32 + 16);
;                 const bf16x8 v0 = __builtin_bit_cast(bf16x8, ((u32x4){a0.x, a0.y, a1.x, a1.y})), v1 = __builtin_bit_cast(bf16x8, ((u32x4){c0.x, c0.y, c1.x, c1.y}));
;                 oa0 = __builtin_amdgcn_mfma_f32_32x32x16_bf16(v0, pfa, oa0, 0, 0, 0);
;                 oa1 = __builtin_amdgcn_mfma_f32_32x32x16_bf16(v1, pfa, oa1, 0, 0, 0);
;                 ob0 = __builtin_amdgcn_mfma_f32_32x32x16_bf16(v0, pfb, ob0, 0, 0, 0);
;                 ob1 = __builtin_amdgcn_mfma_f32_32x32x16_bf16(v1, pfb, ob1, 0, 0, 0);
;             }
	v_mfma_f32_32x32x16_bf16 v[48:63], v[80:83], v[84:87], v[48:63]
	v_cvt_pk_bf16_f32 v65, v222, v223
	v_cvt_pk_bf16_f32 v66, v224, v225
	v_cvt_pk_bf16_f32 v67, v226, v227
	s_waitcnt lgkmcnt(0)
	v_mfma_f32_32x32x16_bf16 v[32:47], v[88:91], v[84:87], v[32:47]
	v_exp_f32_e32 v84, v68
	v_sub_f32_e32 v68, v72, v199
	v_exp_f32_e32 v228, v68
	v_sub_f32_e32 v68, v73, v199
	v_exp_f32_e32 v229, v68
	ds_read2_b64 v[68:71], v183 offset0:12 offset1:14
	v_sub_f32_e32 v72, v75, v199
	v_mfma_f32_32x32x16_bf16 v[16:31], v[80:83], v[64:67], v[16:31]
	ds_read2_b64 v[80:83], v184 offset0:44 offset1:46
	v_exp_f32_e32 v234, v72
	v_sub_f32_e32 v72, v76, v199
	v_exp_f32_e32 v235, v72
	v_sub_f32_e32 v72, v77, v199
	v_mfma_f32_32x32x16_bf16 v[0:15], v[88:91], v[64:67], v[0:15]
	v_sub_f32_e32 v64, v74, v199
	v_exp_f32_e32 v231, v64
	v_cvt_pk_bf16_f32 v64, v230, v232
	v_cvt_pk_bf16_f32 v65, v237, v238
	v_cvt_pk_bf16_f32 v66, v92, v93
	v_cvt_pk_bf16_f32 v67, v94, v84
	v_exp_f32_e32 v230, v72
	v_sub_f32_e32 v72, v78, v199
	s_waitcnt lgkmcnt(1)
	v_mfma_f32_32x32x16_bf16 v[48:63], v[68:71], v[64:67], v[48:63]
	v_exp_f32_e32 v232, v72
	s_waitcnt lgkmcnt(0)
	v_mfma_f32_32x32x16_bf16 v[32:47], v[80:83], v[64:67], v[32:47]
	v_sub_f32_e32 v64, v79, v199
	v_exp_f32_e32 v233, v64
	v_cvt_pk_bf16_f32 v64, v228, v229
	v_cvt_pk_bf16_f32 v65, v231, v234
	v_cvt_pk_bf16_f32 v66, v235, v230
	v_cvt_pk_bf16_f32 v67, v232, v233
	s_nop 1
	v_mfma_f32_32x32x16_bf16 v[16:31], v[68:71], v[64:67], v[16:31]
	v_add_f32_e32 v68, v237, v236
	v_add_f32_e32 v68, v238, v68
	v_add_f32_e32 v68, v92, v68
	v_add_f32_e32 v68, v93, v68
	v_add_f32_e32 v68, v94, v68
	v_add_f32_e32 v68, v84, v68
	v_add_f32_e32 v191, v191, v68
	v_mfma_f32_32x32x16_bf16 v[0:15], v[80:83], v[64:67], v[0:15]
	s_setprio 1
	ds_read_b128 v[64:67], v195 offset:9216
	ds_read_b128 v[236:239], v195 offset:9248
	s_waitcnt lgkmcnt(1)
	v_mfma_f32_32x32x16_bf16 v[112:127], v[64:67], v[146:149], 0
	v_mfma_f32_32x32x16_bf16 v[96:111], v[64:67], v[150:153], 0
	ds_read_b128 v[64:67], v195 offset:13824
	s_waitcnt lgkmcnt(1)
	v_mfma_f32_32x32x16_bf16 v[112:127], v[236:239], v[154:157], v[112:127]
	v_mfma_f32_32x32x16_bf16 v[96:111], v[236:239], v[162:165], v[96:111]
	ds_read_b128 v[236:239], v195 offset:13856
	s_waitcnt lgkmcnt(1)
	v_mfma_f32_32x32x16_bf16 v[80:95], v[64:67], v[146:149], 0
	v_mfma_f32_32x32x16_bf16 v[64:79], v[64:67], v[150:153], 0
	s_waitcnt lgkmcnt(0)
	v_mfma_f32_32x32x16_bf16 v[80:95], v[236:239], v[154:157], v[80:95]
	v_mfma_f32_32x32x16_bf16 v[64:79], v[236:239], v[162:165], v[64:79]
	ds_read_b128 v[236:239], v195 offset:9280
	s_waitcnt lgkmcnt(0)
	v_mfma_f32_32x32x16_bf16 v[112:127], v[236:239], v[158:161], v[112:127]
	v_mfma_f32_32x32x16_bf16 v[96:111], v[236:239], v[170:173], v[96:111]
	ds_read_b128 v[236:239], v195 offset:13888
	s_waitcnt lgkmcnt(0)
	v_mfma_f32_32x32x16_bf16 v[80:95], v[236:239], v[158:161], v[80:95]
	v_mfma_f32_32x32x16_bf16 v[64:79], v[236:239], v[170:173], v[64:79]
	ds_read_b128 v[236:239], v195 offset:9312
	s_waitcnt lgkmcnt(0)
	v_mfma_f32_32x32x16_bf16 v[112:127], v[236:239], v[166:169], v[112:127]
	v_mfma_f32_32x32x16_bf16 v[96:111], v[236:239], v[174:177], v[96:111]
	ds_read_b128 v[236:239], v195 offset:13920
	s_waitcnt lgkmcnt(0)
	v_mfma_f32_32x32x16_bf16 v[80:95], v[236:239], v[166:169], v[80:95]
	v_mfma_f32_32x32x16_bf16 v[64:79], v[236:239], v[174:177], v[64:79]
	s_setprio 0
	s_nop 9
	v_max_f32_e32 v185, v80, v80
	v_max_f32_e32 v195, v112, v112
	v_max_f32_e32 v185, v195, v185
	v_max3_f32 v195, v81, v114, v82
	v_max3_f32 v185, v185, v113, v115
	v_max3_f32 v195, v195, v116, v84
	v_max3_f32 v185, v185, v83, v117
	v_max3_f32 v195, v195, v118, v86
	v_max3_f32 v185, v185, v85, v119
	v_max3_f32 v195, v195, v120, v88
	v_max3_f32 v185, v185, v87, v121
	v_max3_f32 v195, v195, v122, v90
	v_max3_f32 v185, v185, v89, v123
	v_max3_f32 v195, v195, v124, v92
	v_max3_f32 v185, v185, v91, v125
	v_max3_f32 v195, v195, v126, v94
	v_max3_f32 v185, v185, v93, v127
	v_max3_f32 v185, v185, v95, v195
	ds_bpermute_b32 v195, v179, v185
	s_waitcnt lgkmcnt(0)
	v_max3_f32 v185, v204, v185, v195
	v_add_f32_e32 v195, 0x41000000, v204
	v_cmp_gt_f32_e32 vcc, v185, v195
	s_cbranch_vccz .LBB0_374
	v_sub_f32_e32 v195, v204, v185
	v_exp_f32_e32 v204, v195
	s_nop 0
	v_pk_mul_f32 v[62:63], v[62:63], v[204:205] op_sel_hi:[1,0]
	v_pk_mul_f32 v[60:61], v[60:61], v[204:205] op_sel_hi:[1,0]
	v_pk_mul_f32 v[58:59], v[58:59], v[204:205] op_sel_hi:[1,0]
	v_pk_mul_f32 v[56:57], v[56:57], v[204:205] op_sel_hi:[1,0]
	v_pk_mul_f32 v[54:55], v[54:55], v[204:205] op_sel_hi:[1,0]
	v_pk_mul_f32 v[52:53], v[52:53], v[204:205] op_sel_hi:[1,0]
	v_pk_mul_f32 v[50:51], v[50:51], v[204:205] op_sel_hi:[1,0]
	v_pk_mul_f32 v[48:49], v[48:49], v[204:205] op_sel_hi:[1,0]
	v_pk_mul_f32 v[46:47], v[46:47], v[204:205] op_sel_hi:[1,0]
	v_pk_mul_f32 v[44:45], v[44:45], v[204:205] op_sel_hi:[1,0]
	v_pk_mul_f32 v[42:43], v[42:43], v[204:205] op_sel_hi:[1,0]
	v_pk_mul_f32 v[40:41], v[40:41], v[204:205] op_sel_hi:[1,0]
	v_pk_mul_f32 v[38:39], v[38:39], v[204:205] op_sel_hi:[1,0]
	v_pk_mul_f32 v[36:37], v[36:37], v[204:205] op_sel_hi:[1,0]
	v_pk_mul_f32 v[34:35], v[34:35], v[204:205] op_sel_hi:[1,0]
	v_pk_mul_f32 v[32:33], v[32:33], v[204:205] op_sel_hi:[1,0]
	v_mul_f32_e32 v191, v191, v204
	s_branch .LBB0_375

; template <int DK, bool IS_A>
; __device__ __forceinline__ void attn_unit(const Params& P, int l, LAS unsigned char* lds, int b, int grp, int qtok0, int nkeys) {
;     ...
;             AT_SOFTMAX(pa, ma, la, oa0, oa1);
;             AT_SOFTMAX(pb, mb, lb_, ob0, ob1);
.LBB0_375:
	v_add_f32_e32 v187, 0, v187
	v_add_f32_e32 v187, v205, v187
	v_add_f32_e32 v187, v206, v187
	v_add_f32_e32 v187, v207, v187
	v_add_f32_e32 v187, v208, v187
	v_add_f32_e32 v187, v209, v187
	v_add_f32_e32 v187, v210, v187
	v_add_f32_e32 v187, v211, v187
	v_add_f32_e32 v187, v212, v187
	v_add_f32_e32 v187, v213, v187
	v_add_f32_e32 v187, v214, v187
	v_add_f32_e32 v187, v215, v187
	v_add_f32_e32 v187, v216, v187
	v_add_f32_e32 v187, v217, v187
	v_add_f32_e32 v187, v218, v187
	v_add_f32_e32 v187, v219, v187
	v_add_f32_e32 v187, v220, v187
	v_add_f32_e32 v187, v221, v187
	v_max_f32_e32 v195, v64, v64
	v_max_f32_e32 v204, v96, v96
	v_add_f32_e32 v187, v222, v187
	v_max_f32_e32 v195, v204, v195
	v_add_f32_e32 v187, v223, v187
	v_max3_f32 v204, v65, v98, v66
	v_max3_f32 v195, v195, v97, v99
	v_add_f32_e32 v187, v224, v187
	v_max3_f32 v204, v204, v100, v68
	v_max3_f32 v195, v195, v67, v101
	v_add_f32_e32 v187, v225, v187
	v_max3_f32 v204, v204, v102, v70
	v_max3_f32 v195, v195, v69, v103
	v_add_f32_e32 v187, v226, v187
	v_max3_f32 v204, v204, v104, v72
	v_max3_f32 v195, v195, v71, v105
	v_add_f32_e32 v187, v227, v187
	v_max3_f32 v204, v204, v106, v74
	v_max3_f32 v195, v195, v73, v107
	v_add_f32_e32 v187, v228, v187
	v_max3_f32 v204, v204, v108, v76
	v_max3_f32 v195, v195, v75, v109
	v_add_f32_e32 v187, v229, v187
	v_max3_f32 v204, v204, v110, v78
	v_max3_f32 v195, v195, v77, v111
	v_add_f32_e32 v187, v231, v187
	v_max3_f32 v195, v195, v79, v204
	v_add_f32_e32 v187, v234, v187
	ds_bpermute_b32 v204, v179, v195
	v_add_f32_e32 v187, v235, v187
	v_add_f32_e32 v187, v230, v187
	v_add_f32_e32 v187, v232, v187
	v_add_f32_e32 v187, v233, v187
	v_add_f32_e32 v182, v182, v187
	s_waitcnt lgkmcnt(0)
	v_max3_f32 v187, v199, v195, v204
	v_add_f32_e32 v204, 0x41000000, v199
	v_cmp_gt_f32_e32 vcc, v187, v204
	s_cbranch_vccz .LBB0_377
	v_sub_f32_e32 v195, v199, v187
	v_exp_f32_e32 v204, v195
	s_nop 0
	v_pk_mul_f32 v[30:31], v[30:31], v[204:205] op_sel_hi:[1,0]
	v_pk_mul_f32 v[28:29], v[28:29], v[204:205] op_sel_hi:[1,0]
	v_pk_mul_f32 v[26:27], v[26:27], v[204:205] op_sel_hi:[1,0]
	v_pk_mul_f32 v[24:25], v[24:25], v[204:205] op_sel_hi:[1,0]
	v_pk_mul_f32 v[22:23], v[22:23], v[204:205] op_sel_hi:[1,0]
	v_pk_mul_f32 v[20:21], v[20:21], v[204:205] op_sel_hi:[1,0]
	v_pk_mul_f32 v[18:19], v[18:19], v[204:205] op_sel_hi:[1,0]
	v_pk_mul_f32 v[16:17], v[16:17], v[204:205] op_sel_hi:[1,0]
	v_pk_mul_f32 v[14:15], v[14:15], v[204:205] op_sel_hi:[1,0]
	v_pk_mul_f32 v[12:13], v[12:13], v[204:205] op_sel_hi:[1,0]
	v_pk_mul_f32 v[10:11], v[10:11], v[204:205] op_sel_hi:[1,0]
	v_pk_mul_f32 v[8:9], v[8:9], v[204:205] op_sel_hi:[1,0]
	v_pk_mul_f32 v[6:7], v[6:7], v[204:205] op_sel_hi:[1,0]
	v_pk_mul_f32 v[4:5], v[4:5], v[204:205] op_sel_hi:[1,0]
	v_pk_mul_f32 v[2:3], v[2:3], v[204:205] op_sel_hi:[1,0]
	v_pk_mul_f32 v[0:1], v[0:1], v[204:205] op_sel_hi:[1,0]
	v_mul_f32_e32 v182, v182, v204
	s_branch .LBB0_378

; #define LAS __attribute__((address_space(3)))
; #define AT_LOAD(t_) do { const bf16_t* kn = ksrc + (size_t)(t_) * AKT * INW; const bf16_t* vn = vsrc + (t_) * AKT; \
;         kreg0 = *(const u32x4*)kn; kreg1 = *(const u32x4*)(kn + (size_t)64 * INW); vreg0 = *(const u32x4*)vn; vreg1 = *(const u32x4*)(vn + 64); } while (0)
; template <int DK, bool IS_A>
; __device__ __forceinline__ void attn_unit(const Params& P, int l, LAS unsigned char* lds, int b, int grp, int qtok0, int nkeys) {
;     ...
;         const int buf = t & 1;
;         if (t + 1 < NT) AT_LOAD(t + 1);
; #pragma unroll
;         for (int h = 0; h < 2; ++h) {
;             const LAS unsigned char* kb = lds + buf * A_BUF + kfo + h * 64 * AK_PITCH;
;             const LAS unsigned char* vb = lds + buf * A_BUF + vfo + h * 128;
;             f32x16 pa[2], pb[2];
; #pragma unroll
;             for (int jj = 0; jj < 2; ++jj)
; #pragma unroll
;                 for (int r = 0; r < 16; ++r) { pa[jj][r] = 0.f; pb[jj][r] = 0.f; }
;             __builtin_amdgcn_s_setprio(1);
; #pragma unroll
;             for (int i = 0; i < DK / 16; ++i)
; #pragma unroll
;                 for (int jj = 0; jj < 2; ++jj) {
;                     const bf16x8 kf = *(const LAS bf16x8*)(kb + jj * 32 * AK_PITCH + i * 32);
;                     pa[jj] = __builtin_amdgcn_mfma_f32_32x32x16_bf16(kf, qa[i], pa[jj], 0, 0, 0);
;                     pb[jj] = __builtin_amdgcn_mfma_f32_32x32x16_bf16(kf, qb[i], pb[jj], 0, 0, 0);
;                 }
;             __builtin_amdgcn_s_setprio(0);
.LBB0_386:
	s_bitcmp1_b32 s12, 0
	s_cselect_b32 s10, 0x8a00, 0
	s_add_i32 s10, s10, 0
	v_add_u32_e32 v64, s10, v176
	v_add_u32_e32 v186, v64, v178
	s_setprio 1
	ds_read_b128 v[64:67], v186
	ds_read_b128 v[188:191], v186 offset:32
	s_waitcnt lgkmcnt(1)
	v_mfma_f32_32x32x16_bf16 v[112:127], v[64:67], v[142:145], 0
	v_mfma_f32_32x32x16_bf16 v[96:111], v[64:67], v[158:161], 0
	ds_read_b128 v[64:67], v186 offset:4608
	s_waitcnt lgkmcnt(1)
	v_mfma_f32_32x32x16_bf16 v[112:127], v[188:191], v[150:153], v[112:127]
	v_mfma_f32_32x32x16_bf16 v[96:111], v[188:191], v[154:157], v[96:111]
	ds_read_b128 v[188:191], v186 offset:4640
	s_waitcnt lgkmcnt(1)
	v_mfma_f32_32x32x16_bf16 v[80:95], v[64:67], v[142:145], 0
	v_mfma_f32_32x32x16_bf16 v[64:79], v[64:67], v[158:161], 0
	s_waitcnt lgkmcnt(0)
	v_mfma_f32_32x32x16_bf16 v[80:95], v[188:191], v[150:153], v[80:95]
	v_mfma_f32_32x32x16_bf16 v[64:79], v[188:191], v[154:157], v[64:79]
	s_setprio 0
	s_nop 9
	v_max_f32_e32 v180, v80, v80
	v_max_f32_e32 v181, v112, v112
	v_max_f32_e32 v180, v181, v180
	v_max3_f32 v181, v81, v114, v82
	v_max3_f32 v180, v180, v113, v115
	v_max3_f32 v181, v181, v116, v84
	v_max3_f32 v180, v180, v83, v117
	v_max3_f32 v181, v181, v118, v86
	v_max3_f32 v180, v180, v85, v119
	v_max3_f32 v181, v181, v120, v88
	v_max3_f32 v180, v180, v87, v121
	v_max3_f32 v181, v181, v122, v90
	v_max3_f32 v180, v180, v89, v123
	v_max3_f32 v181, v181, v124, v92
	v_max3_f32 v180, v180, v91, v125
	v_max3_f32 v181, v181, v126, v94
	v_max3_f32 v180, v180, v93, v127
	v_max3_f32 v180, v180, v95, v181
	ds_bpermute_b32 v181, v163, v180
	s_waitcnt lgkmcnt(0)
	v_max3_f32 v187, v182, v180, v181
	v_add_f32_e32 v181, 0x41000000, v182
	v_cmp_gt_f32_e32 vcc, v187, v181
	s_cbranch_vccz .LBB0_388
	v_sub_f32_e32 v180, v182, v187
	v_exp_f32_e32 v180, v180
	s_nop 0
	v_pk_mul_f32 v[62:63], v[62:63], v[180:181] op_sel_hi:[1,0]
	v_pk_mul_f32 v[60:61], v[60:61], v[180:181] op_sel_hi:[1,0]
	v_pk_mul_f32 v[58:59], v[58:59], v[180:181] op_sel_hi:[1,0]
	v_pk_mul_f32 v[56:57], v[56:57], v[180:181] op_sel_hi:[1,0]
	v_pk_mul_f32 v[54:55], v[54:55], v[180:181] op_sel_hi:[1,0]
	v_pk_mul_f32 v[52:53], v[52:53], v[180:181] op_sel_hi:[1,0]
	v_pk_mul_f32 v[50:51], v[50:51], v[180:181] op_sel_hi:[1,0]
	v_pk_mul_f32 v[48:49], v[48:49], v[180:181] op_sel_hi:[1,0]
	v_pk_mul_f32 v[46:47], v[46:47], v[180:181] op_sel_hi:[1,0]
	v_pk_mul_f32 v[44:45], v[44:45], v[180:181] op_sel_hi:[1,0]
	v_pk_mul_f32 v[42:43], v[42:43], v[180:181] op_sel_hi:[1,0]
	v_pk_mul_f32 v[40:41], v[40:41], v[180:181] op_sel_hi:[1,0]
	v_pk_mul_f32 v[38:39], v[38:39], v[180:181] op_sel_hi:[1,0]
	v_pk_mul_f32 v[36:37], v[36:37], v[180:181] op_sel_hi:[1,0]
	v_pk_mul_f32 v[34:35], v[34:35], v[180:181] op_sel_hi:[1,0]
	v_pk_mul_f32 v[32:33], v[32:33], v[180:181] op_sel_hi:[1,0]
	v_mul_f32_e32 v184, v184, v180
	s_branch .LBB0_389

; template <int DK, bool IS_A>
; __device__ __forceinline__ void attn_unit(const Params& P, int l, LAS unsigned char* lds, int b, int grp, int qtok0, int nkeys) {
;     ...
;             AT_SOFTMAX(pa, ma, la, oa0, oa1);
;             AT_SOFTMAX(pb, mb, lb_, ob0, ob1);
.LBB0_389:
	v_max_f32_e32 v180, v64, v64
	v_max_f32_e32 v181, v96, v96
	v_max_f32_e32 v180, v181, v180
	v_max3_f32 v181, v65, v98, v66
	v_max3_f32 v180, v180, v97, v99
	v_max3_f32 v181, v181, v100, v68
	v_max3_f32 v180, v180, v67, v101
	v_max3_f32 v181, v181, v102, v70
	v_max3_f32 v180, v180, v69, v103
	v_max3_f32 v181, v181, v104, v72
	v_max3_f32 v180, v180, v71, v105
	v_max3_f32 v181, v181, v106, v74
	v_max3_f32 v180, v180, v73, v107
	v_max3_f32 v181, v181, v108, v76
	v_max3_f32 v180, v180, v75, v109
	v_max3_f32 v181, v181, v110, v78
	v_max3_f32 v180, v180, v77, v111
	v_max3_f32 v180, v180, v79, v181
	ds_bpermute_b32 v181, v163, v180
	s_waitcnt lgkmcnt(0)
	v_max3_f32 v185, v183, v180, v181
	v_add_f32_e32 v181, 0x41000000, v183
	v_cmp_gt_f32_e32 vcc, v185, v181
	s_cbranch_vccz .LBB0_391
	v_sub_f32_e32 v180, v183, v185
	v_exp_f32_e32 v180, v180
	s_nop 0
	v_pk_mul_f32 v[30:31], v[30:31], v[180:181] op_sel_hi:[1,0]
	v_pk_mul_f32 v[28:29], v[28:29], v[180:181] op_sel_hi:[1,0]
	v_pk_mul_f32 v[26:27], v[26:27], v[180:181] op_sel_hi:[1,0]
	v_pk_mul_f32 v[24:25], v[24:25], v[180:181] op_sel_hi:[1,0]
	v_pk_mul_f32 v[22:23], v[22:23], v[180:181] op_sel_hi:[1,0]
	v_pk_mul_f32 v[20:21], v[20:21], v[180:181] op_sel_hi:[1,0]
	v_pk_mul_f32 v[18:19], v[18:19], v[180:181] op_sel_hi:[1,0]
	v_pk_mul_f32 v[16:17], v[16:17], v[180:181] op_sel_hi:[1,0]
	v_pk_mul_f32 v[14:15], v[14:15], v[180:181] op_sel_hi:[1,0]
	v_pk_mul_f32 v[12:13], v[12:13], v[180:181] op_sel_hi:[1,0]
	v_pk_mul_f32 v[10:11], v[10:11], v[180:181] op_sel_hi:[1,0]
	v_pk_mul_f32 v[8:9], v[8:9], v[180:181] op_sel_hi:[1,0]
	v_pk_mul_f32 v[6:7], v[6:7], v[180:181] op_sel_hi:[1,0]
	v_pk_mul_f32 v[4:5], v[4:5], v[180:181] op_sel_hi:[1,0]
	v_pk_mul_f32 v[2:3], v[2:3], v[180:181] op_sel_hi:[1,0]
	v_pk_mul_f32 v[0:1], v[0:1], v[180:181] op_sel_hi:[1,0]
	v_mul_f32_e32 v179, v179, v180
	s_branch .LBB0_392

; #define LAS __attribute__((address_space(3)))
; __device__ __forceinline__ unsigned pk2(float lo, float hi) { f32x2_t v = {lo, hi}; bf16x2_t b = __builtin_convertvector(v, bf16x2_t); return __builtin_bit_cast(unsigned, b); }
; template <int DK, bool IS_A>
; __device__ __forceinline__ void attn_unit(const Params& P, int l, LAS unsigned char* lds, int b, int grp, int qtok0, int nkeys) {
;     ...
;             AT_SOFTMAX(pa, ma, la, oa0, oa1);
;             AT_SOFTMAX(pb, mb, lb_, ob0, ob1);
;     ...
; #pragma unroll
;             for (int ks = 0; ks < 4; ++ks) {
;                 const int o8 = 8 * (ks & 1);
;                 u32x4 w; const f32x16& xa = pa[ks >> 1]; const f32x16& xb = pb[ks >> 1];
;                 w.x = pk2(xa[o8], xa[o8 + 1]); w.y = pk2(xa[o8 + 2], xa[o8 + 3]); w.z = pk2(xa[o8 + 4], xa[o8 + 5]); w.w = pk2(xa[o8 + 6], xa[o8 + 7]);
;                 const bf16x8 pfa = __builtin_bit_cast(bf16x8, w);
;                 w.x = pk2(xb[o8], xb[o8 + 1]); w.y = pk2(xb[o8 + 2], xb[o8 + 3]); w.z = pk2(xb[o8 + 4], xb[o8 + 5]); w.w = pk2(xb[o8 + 6], xb[o8 + 7]);
;                 const bf16x8 pfb = __builtin_bit_cast(bf16x8, w);
;                 const u32x2 a0 = *(const LAS u32x2*)(vb + ks * 32), a1 = *(const LAS u32x2*)(vb + ks * 32 + 16);
;                 const u32x2 c0 = *(const LAS u32x2*)(vb + 32 * AV_PITCH + ks * 32), c1 = *(const LAS u32x2*)(vb + 32 * AV_PITCH + ks * 32 + 16);
;                 const bf16x8 v0 = __builtin_bit_cast(bf16x8, ((u32x4){a0.x, a0.y, a1.x, a1.y})), v1 = __builtin_bit_cast(bf16x8, ((u32x4){c0.x, c0.y, c1.x, c1.y}));
;                 oa0 = __builtin_amdgcn_mfma_f32_32x32x16_bf16(v0, pfa, oa0, 0, 0, 0);
;                 oa1 = __builtin_amdgcn_mfma_f32_32x32x16_bf16(v1, pfa, oa1, 0, 0, 0);
;                 ob0 = __builtin_amdgcn_mfma_f32_32x32x16_bf16(v0, pfb, ob0, 0, 0, 0);
;                 ob1 = __builtin_amdgcn_mfma_f32_32x32x16_bf16(v1, pfb, ob1, 0, 0, 0);
;             }
.LBB0_392:
	v_sub_f32_e32 v112, v112, v187
	v_exp_f32_e32 v112, v112
	v_sub_f32_e32 v113, v113, v187
	v_exp_f32_e32 v113, v113
	v_sub_f32_e32 v114, v114, v187
	v_exp_f32_e32 v114, v114
	v_sub_f32_e32 v115, v115, v187
	v_exp_f32_e32 v115, v115
	v_sub_f32_e32 v116, v116, v187
	v_add_f32_e32 v180, 0, v112
	v_exp_f32_e32 v116, v116
	v_sub_f32_e32 v117, v117, v187
	v_add_f32_e32 v180, v113, v180
	v_exp_f32_e32 v117, v117
	v_sub_f32_e32 v118, v118, v187
	v_add_f32_e32 v180, v114, v180
	v_exp_f32_e32 v118, v118
	v_sub_f32_e32 v119, v119, v187
	v_add_f32_e32 v180, v115, v180
	v_exp_f32_e32 v119, v119
	v_sub_f32_e32 v120, v120, v187
	v_add_f32_e32 v180, v116, v180
	v_exp_f32_e32 v120, v120
	v_sub_f32_e32 v121, v121, v187
	v_add_f32_e32 v180, v117, v180
	v_exp_f32_e32 v121, v121
	v_sub_f32_e32 v122, v122, v187
	v_add_f32_e32 v180, v118, v180
	v_exp_f32_e32 v122, v122
	v_sub_f32_e32 v123, v123, v187
	v_add_f32_e32 v180, v119, v180
	v_exp_f32_e32 v123, v123
	v_sub_f32_e32 v124, v124, v187
	v_add_f32_e32 v180, v120, v180
	v_exp_f32_e32 v124, v124
	v_sub_f32_e32 v125, v125, v187
	v_add_f32_e32 v180, v121, v180
	v_exp_f32_e32 v125, v125
	v_sub_f32_e32 v126, v126, v187
	v_add_f32_e32 v180, v122, v180
	v_exp_f32_e32 v126, v126
	v_sub_f32_e32 v127, v127, v187
	v_add_f32_e32 v180, v123, v180
	v_exp_f32_e32 v127, v127
	v_sub_f32_e32 v80, v80, v187
	v_add_f32_e32 v180, v124, v180
	v_exp_f32_e32 v182, v80
	v_sub_f32_e32 v80, v81, v187
	v_add_f32_e32 v180, v125, v180
	v_exp_f32_e32 v210, v80
	v_sub_f32_e32 v81, v82, v187
	v_add_f32_e32 v80, v126, v180
	v_exp_f32_e32 v211, v81
	v_sub_f32_e32 v81, v83, v187
	v_add_f32_e32 v80, v127, v80
	v_exp_f32_e32 v212, v81
	v_sub_f32_e32 v81, v84, v187
	v_add_f32_e32 v80, v182, v80
	v_exp_f32_e32 v213, v81
	v_sub_f32_e32 v81, v85, v187
	v_add_f32_e32 v80, v210, v80
	v_exp_f32_e32 v214, v81
	v_sub_f32_e32 v81, v86, v187
	v_add_f32_e32 v80, v211, v80
	v_exp_f32_e32 v215, v81
	v_sub_f32_e32 v81, v87, v187
	v_add_f32_e32 v80, v212, v80
	v_exp_f32_e32 v216, v81
	v_sub_f32_e32 v81, v88, v187
	v_add_f32_e32 v80, v213, v80
	v_exp_f32_e32 v217, v81
	v_sub_f32_e32 v81, v89, v187
	v_add_f32_e32 v80, v214, v80
	v_exp_f32_e32 v219, v81
	v_add_f32_e32 v80, v215, v80
	v_add_f32_e32 v80, v216, v80
	v_add_f32_e32 v80, v217, v80
	v_add_f32_e32 v223, v219, v80
	v_sub_f32_e32 v80, v90, v187
	v_exp_f32_e32 v224, v80
	v_sub_f32_e32 v80, v91, v187
	v_exp_f32_e32 v225, v80
	v_sub_f32_e32 v80, v92, v187
	v_exp_f32_e32 v92, v80
	v_add_u32_e32 v80, s10, v177
	v_sub_f32_e32 v81, v96, v185
	v_add_u32_e32 v88, v80, v164
	v_exp_f32_e32 v183, v81
	v_sub_f32_e32 v81, v97, v185
	v_add_u32_e32 v180, 0x4800, v88
	v_add_u32_e32 v181, 0x6800, v88
	v_exp_f32_e32 v188, v81
	ds_read2_b64 v[80:83], v180 offset1:2
	ds_read2_b64 v[88:91], v181 offset0:32 offset1:34
	v_sub_f32_e32 v96, v99, v185
	v_sub_f32_e32 v84, v98, v185
	v_exp_f32_e32 v190, v96
	v_sub_f32_e32 v96, v100, v185
	v_exp_f32_e32 v189, v84
	v_cvt_pk_bf16_f32 v84, v112, v113
	v_cvt_pk_bf16_f32 v85, v114, v115
	v_cvt_pk_bf16_f32 v86, v116, v117
	v_cvt_pk_bf16_f32 v87, v118, v119
	v_exp_f32_e32 v191, v96
	v_sub_f32_e32 v96, v101, v185
	s_waitcnt lgkmcnt(1)
	v_mfma_f32_32x32x16_bf16 v[48:63], v[80:83], v[84:87], v[48:63]
	v_exp_f32_e32 v192, v96
	v_sub_f32_e32 v96, v102, v185
	v_exp_f32_e32 v193, v96
	v_sub_f32_e32 v96, v107, v185
	v_exp_f32_e32 v198, v96
	v_sub_f32_e32 v96, v108, v185
	v_exp_f32_e32 v199, v96
	s_waitcnt lgkmcnt(0)
	v_mfma_f32_32x32x16_bf16 v[32:47], v[88:91], v[84:87], v[32:47]
	v_sub_f32_e32 v84, v103, v185
	v_exp_f32_e32 v194, v84
	v_cvt_pk_bf16_f32 v84, v183, v188
	v_cvt_pk_bf16_f32 v85, v189, v190
	v_cvt_pk_bf16_f32 v86, v191, v192
	v_cvt_pk_bf16_f32 v87, v193, v194
	v_sub_f32_e32 v96, v109, v185
	v_exp_f32_e32 v204, v96
	v_mfma_f32_32x32x16_bf16 v[16:31], v[80:83], v[84:87], v[16:31]
	v_sub_f32_e32 v80, v93, v187
	v_exp_f32_e32 v93, v80
	v_sub_f32_e32 v80, v104, v185
	v_exp_f32_e32 v195, v80
	v_sub_f32_e32 v80, v105, v185
	v_exp_f32_e32 v196, v80
	ds_read2_b64 v[80:83], v180 offset0:4 offset1:6
	v_mfma_f32_32x32x16_bf16 v[0:15], v[88:91], v[84:87], v[0:15]
	ds_read2_b64 v[88:91], v181 offset0:36 offset1:38
	v_sub_f32_e32 v84, v106, v185
	v_exp_f32_e32 v197, v84
	v_cvt_pk_bf16_f32 v84, v120, v121
	v_cvt_pk_bf16_f32 v85, v122, v123
	v_cvt_pk_bf16_f32 v86, v124, v125
	v_cvt_pk_bf16_f32 v87, v126, v127
	v_sub_f32_e32 v96, v110, v185
	v_exp_f32_e32 v205, v96
	s_waitcnt lgkmcnt(1)
	v_mfma_f32_32x32x16_bf16 v[48:63], v[80:83], v[84:87], v[48:63]
	v_sub_f32_e32 v64, v64, v185
	v_exp_f32_e32 v207, v64
	v_sub_f32_e32 v64, v65, v185
	v_exp_f32_e32 v208, v64
	v_sub_f32_e32 v64, v66, v185
	v_exp_f32_e32 v209, v64
	v_sub_f32_e32 v64, v67, v185
	s_waitcnt lgkmcnt(0)
; #define LAS __attribute__((address_space(3)))
; template <int DK, bool IS_A>
; __device__ __forceinline__ void attn_unit(const Params& P, int l, LAS unsigned char* lds, int b, int grp, int qtok0, int nkeys) {
;     ...
;             __builtin_amdgcn_s_setprio(1);
; #pragma unroll
;             for (int i = 0; i < DK / 16; ++i)
; #pragma unroll
;                 for (int jj = 0; jj < 2; ++jj) {
;                     const bf16x8 kf = *(const LAS bf16x8*)(kb + jj * 32 * AK_PITCH + i * 32);
;                     pa[jj] = __builtin_amdgcn_mfma_f32_32x32x16_bf16(kf, qa[i], pa[jj], 0, 0, 0);
;                     pb[jj] = __builtin_amdgcn_mfma_f32_32x32x16_bf16(kf, qb[i], pb[jj], 0, 0, 0);
;                 }
;             __builtin_amdgcn_s_setprio(0);
;     ...
;             AT_SOFTMAX(pa, ma, la, oa0, oa1);
;             AT_SOFTMAX(pb, mb, lb_, ob0, ob1);
;     ...
; #pragma unroll
;             for (int ks = 0; ks < 4; ++ks) {
;                 const int o8 = 8 * (ks & 1);
;                 u32x4 w; const f32x16& xa = pa[ks >> 1]; const f32x16& xb = pb[ks >> 1];
;                 w.x = pk2(xa[o8], xa[o8 + 1]); w.y = pk2(xa[o8 + 2], xa[o8 + 3]); w.z = pk2(xa[o8 + 4], xa[o8 + 5]); w.w = pk2(xa[o8 + 6], xa[o8 + 7]);
;                 const bf16x8 pfa = __builtin_bit_cast(bf16x8, w);
;                 w.x = pk2(xb[o8], xb[o8 + 1]); w.y = pk2(xb[o8 + 2], xb[o8 + 3]); w.z = pk2(xb[o8 + 4], xb[o8 + 5]); w.w = pk2(xb[o8 + 6], xb[o8 + 7]);
;                 const bf16x8 pfb = __builtin_bit_cast(bf16x8, w);
;                 const u32x2 a0 = *(const LAS u32x2*)(vb + ks * 32), a1 = *(const LAS u32x2*)(vb + ks * 32 + 16);
;                 const u32x2 c0 = *(const LAS u32x2*)(vb + 32 * AV_PITCH + ks * 32), c1 = *(const LAS u32x2*)(vb + 32 * AV_PITCH + ks * 32 + 16);
;                 const bf16x8 v0 = __builtin_bit_cast(bf16x8, ((u32x4){a0.x, a0.y, a1.x, a1.y})), v1 = __builtin_bit_cast(bf16x8, ((u32x4){c0.x, c0.y, c1.x, c1.y}));
;                 oa0 = __builtin_amdgcn_mfma_f32_32x32x16_bf16(v0, pfa, oa0, 0, 0, 0);
;                 oa1 = __builtin_amdgcn_mfma_f32_32x32x16_bf16(v1, pfa, oa1, 0, 0, 0);
;                 ob0 = __builtin_amdgcn_mfma_f32_32x32x16_bf16(v0, pfb, ob0, 0, 0, 0);
;                 ob1 = __builtin_amdgcn_mfma_f32_32x32x16_bf16(v1, pfb, ob1, 0, 0, 0);
;             }
	v_mfma_f32_32x32x16_bf16 v[32:47], v[88:91], v[84:87], v[32:47]
	v_sub_f32_e32 v84, v111, v185
	v_exp_f32_e32 v206, v84
	v_cvt_pk_bf16_f32 v84, v195, v196
	v_cvt_pk_bf16_f32 v85, v197, v198
	v_cvt_pk_bf16_f32 v86, v199, v204
	v_cvt_pk_bf16_f32 v87, v205, v206
	s_nop 1
	v_mfma_f32_32x32x16_bf16 v[16:31], v[80:83], v[84:87], v[16:31]
	v_sub_f32_e32 v80, v94, v187
	v_exp_f32_e32 v94, v80
	ds_read2_b64 v[80:83], v180 offset0:8 offset1:10
	v_mfma_f32_32x32x16_bf16 v[0:15], v[88:91], v[84:87], v[0:15]
	ds_read2_b64 v[88:91], v181 offset0:40 offset1:42
	v_cvt_pk_bf16_f32 v84, v182, v210
	v_exp_f32_e32 v210, v64
	v_sub_f32_e32 v64, v68, v185
	v_cvt_pk_bf16_f32 v85, v211, v212
	v_exp_f32_e32 v211, v64
	v_sub_f32_e32 v64, v69, v185
	v_exp_f32_e32 v212, v64
	v_sub_f32_e32 v64, v70, v185
	v_cvt_pk_bf16_f32 v86, v213, v214
	v_exp_f32_e32 v213, v64
	v_sub_f32_e32 v64, v71, v185
	v_exp_f32_e32 v214, v64
	v_cvt_pk_bf16_f32 v87, v215, v216
	v_sub_f32_e32 v68, v95, v187
	v_cvt_pk_bf16_f32 v64, v207, v208
	s_waitcnt lgkmcnt(1)
	v_mfma_f32_32x32x16_bf16 v[48:63], v[80:83], v[84:87], v[48:63]
	v_cvt_pk_bf16_f32 v65, v209, v210
	v_cvt_pk_bf16_f32 v66, v211, v212
	v_cvt_pk_bf16_f32 v67, v213, v214
	s_waitcnt lgkmcnt(0)
	v_mfma_f32_32x32x16_bf16 v[32:47], v[88:91], v[84:87], v[32:47]
	v_exp_f32_e32 v84, v68
	v_sub_f32_e32 v68, v72, v185
	v_exp_f32_e32 v215, v68
	v_sub_f32_e32 v68, v73, v185
	v_exp_f32_e32 v216, v68
	ds_read2_b64 v[68:71], v180 offset0:12 offset1:14
	v_sub_f32_e32 v72, v75, v185
	v_mfma_f32_32x32x16_bf16 v[16:31], v[80:83], v[64:67], v[16:31]
	ds_read2_b64 v[80:83], v181 offset0:44 offset1:46
	v_exp_f32_e32 v221, v72
	v_sub_f32_e32 v72, v76, v185
	v_exp_f32_e32 v222, v72
	v_sub_f32_e32 v72, v77, v185
	v_mfma_f32_32x32x16_bf16 v[0:15], v[88:91], v[64:67], v[0:15]
	v_sub_f32_e32 v64, v74, v185
	v_exp_f32_e32 v218, v64
	v_cvt_pk_bf16_f32 v64, v217, v219
	v_cvt_pk_bf16_f32 v65, v224, v225
	v_cvt_pk_bf16_f32 v66, v92, v93
	v_cvt_pk_bf16_f32 v67, v94, v84
	v_exp_f32_e32 v217, v72
	v_sub_f32_e32 v72, v78, v185
	s_waitcnt lgkmcnt(1)
	v_mfma_f32_32x32x16_bf16 v[48:63], v[68:71], v[64:67], v[48:63]
	v_exp_f32_e32 v219, v72
	s_waitcnt lgkmcnt(0)
	v_mfma_f32_32x32x16_bf16 v[32:47], v[80:83], v[64:67], v[32:47]
	v_sub_f32_e32 v64, v79, v185
	v_exp_f32_e32 v220, v64
	v_cvt_pk_bf16_f32 v64, v215, v216
	v_cvt_pk_bf16_f32 v65, v218, v221
	v_cvt_pk_bf16_f32 v66, v222, v217
	v_cvt_pk_bf16_f32 v67, v219, v220
	s_nop 1
	v_mfma_f32_32x32x16_bf16 v[16:31], v[68:71], v[64:67], v[16:31]
	v_add_f32_e32 v68, v224, v223
	v_add_f32_e32 v68, v225, v68
	v_add_f32_e32 v68, v92, v68
	v_add_f32_e32 v68, v93, v68
	v_add_f32_e32 v68, v94, v68
	v_add_f32_e32 v68, v84, v68
	v_add_f32_e32 v184, v184, v68
	v_mfma_f32_32x32x16_bf16 v[0:15], v[80:83], v[64:67], v[0:15]
	s_setprio 1
	ds_read_b128 v[64:67], v186 offset:9216
	ds_read_b128 v[224:227], v186 offset:9248
	s_waitcnt lgkmcnt(1)
	v_mfma_f32_32x32x16_bf16 v[112:127], v[64:67], v[142:145], 0
	v_mfma_f32_32x32x16_bf16 v[96:111], v[64:67], v[158:161], 0
	ds_read_b128 v[64:67], v186 offset:13824
	s_waitcnt lgkmcnt(1)
	v_mfma_f32_32x32x16_bf16 v[112:127], v[224:227], v[150:153], v[112:127]
	v_mfma_f32_32x32x16_bf16 v[96:111], v[224:227], v[154:157], v[96:111]
	ds_read_b128 v[224:227], v186 offset:13856
	s_waitcnt lgkmcnt(1)
	v_mfma_f32_32x32x16_bf16 v[80:95], v[64:67], v[142:145], 0
	v_mfma_f32_32x32x16_bf16 v[64:79], v[64:67], v[158:161], 0
	s_waitcnt lgkmcnt(0)
	v_mfma_f32_32x32x16_bf16 v[80:95], v[224:227], v[150:153], v[80:95]
	v_mfma_f32_32x32x16_bf16 v[64:79], v[224:227], v[154:157], v[64:79]
	s_setprio 0
	s_nop 9
	v_max_f32_e32 v182, v80, v80
	v_max_f32_e32 v186, v112, v112
	v_max_f32_e32 v182, v186, v182
	v_max3_f32 v186, v81, v114, v82
	v_max3_f32 v182, v182, v113, v115
	v_max3_f32 v186, v186, v116, v84
	v_max3_f32 v182, v182, v83, v117
	v_max3_f32 v186, v186, v118, v86
	v_max3_f32 v182, v182, v85, v119
	v_max3_f32 v186, v186, v120, v88
	v_max3_f32 v182, v182, v87, v121
	v_max3_f32 v186, v186, v122, v90
	v_max3_f32 v182, v182, v89, v123
	v_max3_f32 v186, v186, v124, v92
	v_max3_f32 v182, v182, v91, v125
	v_max3_f32 v186, v186, v126, v94
	v_max3_f32 v182, v182, v93, v127
	v_max3_f32 v182, v182, v95, v186
	ds_bpermute_b32 v186, v163, v182
	s_waitcnt lgkmcnt(0)
	v_max3_f32 v182, v187, v182, v186
	v_add_f32_e32 v186, 0x41000000, v187
	v_cmp_gt_f32_e32 vcc, v182, v186
	s_cbranch_vccz .LBB0_394
	v_sub_f32_e32 v186, v187, v182
	v_exp_f32_e32 v186, v186
	s_nop 0
	v_pk_mul_f32 v[62:63], v[62:63], v[186:187] op_sel_hi:[1,0]
	v_pk_mul_f32 v[60:61], v[60:61], v[186:187] op_sel_hi:[1,0]
	v_pk_mul_f32 v[58:59], v[58:59], v[186:187] op_sel_hi:[1,0]
	v_pk_mul_f32 v[56:57], v[56:57], v[186:187] op_sel_hi:[1,0]
	v_pk_mul_f32 v[54:55], v[54:55], v[186:187] op_sel_hi:[1,0]
	v_pk_mul_f32 v[52:53], v[52:53], v[186:187] op_sel_hi:[1,0]
	v_pk_mul_f32 v[50:51], v[50:51], v[186:187] op_sel_hi:[1,0]
	v_pk_mul_f32 v[48:49], v[48:49], v[186:187] op_sel_hi:[1,0]
	v_pk_mul_f32 v[46:47], v[46:47], v[186:187] op_sel_hi:[1,0]
	v_pk_mul_f32 v[44:45], v[44:45], v[186:187] op_sel_hi:[1,0]
	v_pk_mul_f32 v[42:43], v[42:43], v[186:187] op_sel_hi:[1,0]
	v_pk_mul_f32 v[40:41], v[40:41], v[186:187] op_sel_hi:[1,0]
	v_pk_mul_f32 v[38:39], v[38:39], v[186:187] op_sel_hi:[1,0]
	v_pk_mul_f32 v[36:37], v[36:37], v[186:187] op_sel_hi:[1,0]
	v_pk_mul_f32 v[34:35], v[34:35], v[186:187] op_sel_hi:[1,0]
	v_pk_mul_f32 v[32:33], v[32:33], v[186:187] op_sel_hi:[1,0]
	v_mul_f32_e32 v184, v184, v186
	s_branch .LBB0_395

; template <int DK, bool IS_A>
; __device__ __forceinline__ void attn_unit(const Params& P, int l, LAS unsigned char* lds, int b, int grp, int qtok0, int nkeys) {
;     ...
;             AT_SOFTMAX(pa, ma, la, oa0, oa1);
;             AT_SOFTMAX(pb, mb, lb_, ob0, ob1);
.LBB0_395:
	v_add_f32_e32 v183, 0, v183
	v_add_f32_e32 v183, v188, v183
	v_add_f32_e32 v183, v189, v183
	v_add_f32_e32 v183, v190, v183
	v_add_f32_e32 v183, v191, v183
	v_add_f32_e32 v183, v192, v183
	v_add_f32_e32 v183, v193, v183
	v_add_f32_e32 v183, v194, v183
	v_add_f32_e32 v183, v195, v183
	v_add_f32_e32 v183, v196, v183
	v_add_f32_e32 v183, v197, v183
	v_add_f32_e32 v183, v198, v183
	v_add_f32_e32 v183, v199, v183
	v_add_f32_e32 v183, v204, v183
	v_add_f32_e32 v183, v205, v183
	v_add_f32_e32 v183, v206, v183
	v_add_f32_e32 v183, v207, v183
	v_add_f32_e32 v183, v208, v183
	v_max_f32_e32 v186, v64, v64
	v_max_f32_e32 v187, v96, v96
	v_add_f32_e32 v183, v209, v183
	v_max_f32_e32 v186, v187, v186
	v_add_f32_e32 v183, v210, v183
	v_max3_f32 v187, v65, v98, v66
	v_max3_f32 v186, v186, v97, v99
	v_add_f32_e32 v183, v211, v183
	v_max3_f32 v187, v187, v100, v68
	v_max3_f32 v186, v186, v67, v101
	v_add_f32_e32 v183, v212, v183
	v_max3_f32 v187, v187, v102, v70
	v_max3_f32 v186, v186, v69, v103
	v_add_f32_e32 v183, v213, v183
	v_max3_f32 v187, v187, v104, v72
	v_max3_f32 v186, v186, v71, v105
	v_add_f32_e32 v183, v214, v183
	v_max3_f32 v187, v187, v106, v74
	v_max3_f32 v186, v186, v73, v107
	v_add_f32_e32 v183, v215, v183
	v_max3_f32 v187, v187, v108, v76
	v_max3_f32 v186, v186, v75, v109
	v_add_f32_e32 v183, v216, v183
	v_max3_f32 v187, v187, v110, v78
	v_max3_f32 v186, v186, v77, v111
	v_add_f32_e32 v183, v218, v183
	v_max3_f32 v186, v186, v79, v187
	v_add_f32_e32 v183, v221, v183
	ds_bpermute_b32 v187, v163, v186
	v_add_f32_e32 v183, v222, v183
	v_add_f32_e32 v183, v217, v183
	v_add_f32_e32 v183, v219, v183
	v_add_f32_e32 v183, v220, v183
	v_add_f32_e32 v179, v179, v183
	s_waitcnt lgkmcnt(0)
	v_max3_f32 v183, v185, v186, v187
	v_add_f32_e32 v187, 0x41000000, v185
	v_cmp_gt_f32_e32 vcc, v183, v187
	s_cbranch_vccz .LBB0_397
	v_sub_f32_e32 v185, v185, v183
	v_exp_f32_e32 v186, v185
	s_nop 0
	v_pk_mul_f32 v[30:31], v[30:31], v[186:187] op_sel_hi:[1,0]
	v_pk_mul_f32 v[28:29], v[28:29], v[186:187] op_sel_hi:[1,0]
	v_pk_mul_f32 v[26:27], v[26:27], v[186:187] op_sel_hi:[1,0]
	v_pk_mul_f32 v[24:25], v[24:25], v[186:187] op_sel_hi:[1,0]
	v_pk_mul_f32 v[22:23], v[22:23], v[186:187] op_sel_hi:[1,0]
	v_pk_mul_f32 v[20:21], v[20:21], v[186:187] op_sel_hi:[1,0]
	v_pk_mul_f32 v[18:19], v[18:19], v[186:187] op_sel_hi:[1,0]
	v_pk_mul_f32 v[16:17], v[16:17], v[186:187] op_sel_hi:[1,0]
	v_pk_mul_f32 v[14:15], v[14:15], v[186:187] op_sel_hi:[1,0]
	v_pk_mul_f32 v[12:13], v[12:13], v[186:187] op_sel_hi:[1,0]
	v_pk_mul_f32 v[10:11], v[10:11], v[186:187] op_sel_hi:[1,0]
	v_pk_mul_f32 v[8:9], v[8:9], v[186:187] op_sel_hi:[1,0]
	v_pk_mul_f32 v[6:7], v[6:7], v[186:187] op_sel_hi:[1,0]
	v_pk_mul_f32 v[4:5], v[4:5], v[186:187] op_sel_hi:[1,0]
	v_pk_mul_f32 v[2:3], v[2:3], v[186:187] op_sel_hi:[1,0]
	v_pk_mul_f32 v[0:1], v[0:1], v[186:187] op_sel_hi:[1,0]
	v_mul_f32_e32 v179, v179, v186
	s_branch .LBB0_398

; #define LAS __attribute__((address_space(3)))
; template <int DK, bool IS_A>
; __device__ __forceinline__ void attn_unit(const Params& P, int l, LAS unsigned char* lds, int b, int grp, int qtok0, int nkeys) {
;     ...
;         for (int h = 0; h < 2; ++h) {
;             const LAS unsigned char* kb = lds + buf * A_BUF + kfo + h * 64 * AK_PITCH;
;             const LAS unsigned char* vb = lds + buf * A_BUF + vfo + h * 128;
;             f32x16 pa[2], pb[2];
; #pragma unroll
;             for (int jj = 0; jj < 2; ++jj)
; #pragma unroll
;                 for (int r = 0; r < 16; ++r) { pa[jj][r] = 0.f; pb[jj][r] = 0.f; }
;             __builtin_amdgcn_s_setprio(1);
; #pragma unroll
;             for (int i = 0; i < DK / 16; ++i)
; #pragma unroll
;                 for (int jj = 0; jj < 2; ++jj) {
;                     const bf16x8 kf = *(const LAS bf16x8*)(kb + jj * 32 * AK_PITCH + i * 32);
;                     pa[jj] = __builtin_amdgcn_mfma_f32_32x32x16_bf16(kf, qa[i], pa[jj], 0, 0, 0);
;                     pb[jj] = __builtin_amdgcn_mfma_f32_32x32x16_bf16(kf, qb[i], pb[jj], 0, 0, 0);
;                 }
;             __builtin_amdgcn_s_setprio(0);
.LBB0_420:
	s_mov_b32 s12, s100
	v_add_u32_e32 v64, s12, v177
	v_add_u32_e32 v187, v64, v179
	s_setprio 1
	ds_read_b128 v[64:67], v187
	ds_read_b128 v[188:191], v187 offset:32
	s_waitcnt lgkmcnt(1)
	v_mfma_f32_32x32x16_bf16 v[112:127], v[64:67], v[138:141], 0
	v_mfma_f32_32x32x16_bf16 v[96:111], v[64:67], v[146:149], 0
	ds_read_b128 v[64:67], v187 offset:4608
	s_waitcnt lgkmcnt(1)
	v_mfma_f32_32x32x16_bf16 v[112:127], v[188:191], v[142:145], v[112:127]
	v_mfma_f32_32x32x16_bf16 v[96:111], v[188:191], v[150:153], v[96:111]
	ds_read_b128 v[188:191], v187 offset:4640
	s_waitcnt lgkmcnt(1)
	v_mfma_f32_32x32x16_bf16 v[80:95], v[64:67], v[138:141], 0
	v_mfma_f32_32x32x16_bf16 v[64:79], v[64:67], v[146:149], 0
	s_waitcnt lgkmcnt(0)
	v_mfma_f32_32x32x16_bf16 v[80:95], v[188:191], v[142:145], v[80:95]
	v_mfma_f32_32x32x16_bf16 v[64:79], v[188:191], v[150:153], v[64:79]
	s_setprio 0
	s_nop 9
	v_max_f32_e32 v182, v80, v80
	v_max_f32_e32 v183, v112, v112
	v_max_f32_e32 v182, v183, v182
	v_max3_f32 v183, v81, v114, v82
	v_max3_f32 v182, v182, v113, v115
	v_max3_f32 v183, v183, v116, v84
	v_max3_f32 v182, v182, v83, v117
	v_max3_f32 v183, v183, v118, v86
	v_max3_f32 v182, v182, v85, v119
	v_max3_f32 v183, v183, v120, v88
	v_max3_f32 v182, v182, v87, v121
	v_max3_f32 v183, v183, v122, v90
	v_max3_f32 v182, v182, v89, v123
	v_max3_f32 v183, v183, v124, v92
	v_max3_f32 v182, v182, v91, v125
	v_max3_f32 v183, v183, v126, v94
	v_max3_f32 v182, v182, v93, v127
	v_max3_f32 v182, v182, v95, v183
	ds_bpermute_b32 v183, v163, v182
	s_waitcnt lgkmcnt(0)
	v_max3_f32 v188, v181, v182, v183
	v_add_f32_e32 v183, 0x41000000, v181
	v_cmp_gt_f32_e32 vcc, v188, v183
	s_cbranch_vccz .LBB0_422
	v_sub_f32_e32 v181, v181, v188
	v_exp_f32_e32 v182, v181
	s_nop 0
	v_pk_mul_f32 v[62:63], v[62:63], v[182:183] op_sel_hi:[1,0]
	v_pk_mul_f32 v[60:61], v[60:61], v[182:183] op_sel_hi:[1,0]
	v_pk_mul_f32 v[58:59], v[58:59], v[182:183] op_sel_hi:[1,0]
	v_pk_mul_f32 v[56:57], v[56:57], v[182:183] op_sel_hi:[1,0]
	v_pk_mul_f32 v[54:55], v[54:55], v[182:183] op_sel_hi:[1,0]
	v_pk_mul_f32 v[52:53], v[52:53], v[182:183] op_sel_hi:[1,0]
	v_pk_mul_f32 v[50:51], v[50:51], v[182:183] op_sel_hi:[1,0]
	v_pk_mul_f32 v[48:49], v[48:49], v[182:183] op_sel_hi:[1,0]
	v_pk_mul_f32 v[46:47], v[46:47], v[182:183] op_sel_hi:[1,0]
	v_pk_mul_f32 v[44:45], v[44:45], v[182:183] op_sel_hi:[1,0]
	v_pk_mul_f32 v[42:43], v[42:43], v[182:183] op_sel_hi:[1,0]
	v_pk_mul_f32 v[40:41], v[40:41], v[182:183] op_sel_hi:[1,0]
	v_pk_mul_f32 v[38:39], v[38:39], v[182:183] op_sel_hi:[1,0]
	v_pk_mul_f32 v[36:37], v[36:37], v[182:183] op_sel_hi:[1,0]
	v_pk_mul_f32 v[34:35], v[34:35], v[182:183] op_sel_hi:[1,0]
	v_pk_mul_f32 v[32:33], v[32:33], v[182:183] op_sel_hi:[1,0]
	v_mul_f32_e32 v185, v185, v182
	s_branch .LBB0_423

; template <int DK, bool IS_A>
; __device__ __forceinline__ void attn_unit(const Params& P, int l, LAS unsigned char* lds, int b, int grp, int qtok0, int nkeys) {
;     ...
;             AT_SOFTMAX(pa, ma, la, oa0, oa1);
;             AT_SOFTMAX(pb, mb, lb_, ob0, ob1);
.LBB0_423:
	v_max_f32_e32 v181, v64, v64
	v_max_f32_e32 v182, v96, v96
	v_max_f32_e32 v181, v182, v181
	v_max3_f32 v182, v65, v98, v66
	v_max3_f32 v181, v181, v97, v99
	v_max3_f32 v182, v182, v100, v68
	v_max3_f32 v181, v181, v67, v101
	v_max3_f32 v182, v182, v102, v70
	v_max3_f32 v181, v181, v69, v103
	v_max3_f32 v182, v182, v104, v72
	v_max3_f32 v181, v181, v71, v105
	v_max3_f32 v182, v182, v106, v74
	v_max3_f32 v181, v181, v73, v107
	v_max3_f32 v182, v182, v108, v76
	v_max3_f32 v181, v181, v75, v109
	v_max3_f32 v182, v182, v110, v78
	v_max3_f32 v181, v181, v77, v111
	v_max3_f32 v181, v181, v79, v182
	ds_bpermute_b32 v182, v163, v181
	s_waitcnt lgkmcnt(0)
	v_max3_f32 v186, v184, v181, v182
	v_add_f32_e32 v182, 0x41000000, v184
	v_cmp_gt_f32_e32 vcc, v186, v182
	s_cbranch_vccz .LBB0_425
	v_sub_f32_e32 v181, v184, v186
	v_exp_f32_e32 v182, v181
	s_nop 0
	v_pk_mul_f32 v[30:31], v[30:31], v[182:183] op_sel_hi:[1,0]
	v_pk_mul_f32 v[28:29], v[28:29], v[182:183] op_sel_hi:[1,0]
	v_pk_mul_f32 v[26:27], v[26:27], v[182:183] op_sel_hi:[1,0]
	v_pk_mul_f32 v[24:25], v[24:25], v[182:183] op_sel_hi:[1,0]
	v_pk_mul_f32 v[22:23], v[22:23], v[182:183] op_sel_hi:[1,0]
	v_pk_mul_f32 v[20:21], v[20:21], v[182:183] op_sel_hi:[1,0]
	v_pk_mul_f32 v[18:19], v[18:19], v[182:183] op_sel_hi:[1,0]
	v_pk_mul_f32 v[16:17], v[16:17], v[182:183] op_sel_hi:[1,0]
	v_pk_mul_f32 v[14:15], v[14:15], v[182:183] op_sel_hi:[1,0]
	v_pk_mul_f32 v[12:13], v[12:13], v[182:183] op_sel_hi:[1,0]
	v_pk_mul_f32 v[10:11], v[10:11], v[182:183] op_sel_hi:[1,0]
	v_pk_mul_f32 v[8:9], v[8:9], v[182:183] op_sel_hi:[1,0]
	v_pk_mul_f32 v[6:7], v[6:7], v[182:183] op_sel_hi:[1,0]
	v_pk_mul_f32 v[4:5], v[4:5], v[182:183] op_sel_hi:[1,0]
	v_pk_mul_f32 v[2:3], v[2:3], v[182:183] op_sel_hi:[1,0]
	v_pk_mul_f32 v[0:1], v[0:1], v[182:183] op_sel_hi:[1,0]
	v_mul_f32_e32 v180, v180, v182
	s_branch .LBB0_426

; #define LAS __attribute__((address_space(3)))
; __device__ __forceinline__ unsigned pk2(float lo, float hi) { f32x2_t v = {lo, hi}; bf16x2_t b = __builtin_convertvector(v, bf16x2_t); return __builtin_bit_cast(unsigned, b); }
; template <int DK, bool IS_A>
; __device__ __forceinline__ void attn_unit(const Params& P, int l, LAS unsigned char* lds, int b, int grp, int qtok0, int nkeys) {
;     ...
;             AT_SOFTMAX(pa, ma, la, oa0, oa1);
;             AT_SOFTMAX(pb, mb, lb_, ob0, ob1);
;     ...
; #pragma unroll
;             for (int ks = 0; ks < 4; ++ks) {
;                 const int o8 = 8 * (ks & 1);
;                 u32x4 w; const f32x16& xa = pa[ks >> 1]; const f32x16& xb = pb[ks >> 1];
;                 w.x = pk2(xa[o8], xa[o8 + 1]); w.y = pk2(xa[o8 + 2], xa[o8 + 3]); w.z = pk2(xa[o8 + 4], xa[o8 + 5]); w.w = pk2(xa[o8 + 6], xa[o8 + 7]);
;                 const bf16x8 pfa = __builtin_bit_cast(bf16x8, w);
;                 w.x = pk2(xb[o8], xb[o8 + 1]); w.y = pk2(xb[o8 + 2], xb[o8 + 3]); w.z = pk2(xb[o8 + 4], xb[o8 + 5]); w.w = pk2(xb[o8 + 6], xb[o8 + 7]);
;                 const bf16x8 pfb = __builtin_bit_cast(bf16x8, w);
;                 const u32x2 a0 = *(const LAS u32x2*)(vb + ks * 32), a1 = *(const LAS u32x2*)(vb + ks * 32 + 16);
;                 const u32x2 c0 = *(const LAS u32x2*)(vb + 32 * AV_PITCH + ks * 32), c1 = *(const LAS u32x2*)(vb + 32 * AV_PITCH + ks * 32 + 16);
;                 const bf16x8 v0 = __builtin_bit_cast(bf16x8, ((u32x4){a0.x, a0.y, a1.x, a1.y})), v1 = __builtin_bit_cast(bf16x8, ((u32x4){c0.x, c0.y, c1.x, c1.y}));
;                 oa0 = __builtin_amdgcn_mfma_f32_32x32x16_bf16(v0, pfa, oa0, 0, 0, 0);
;                 oa1 = __builtin_amdgcn_mfma_f32_32x32x16_bf16(v1, pfa, oa1, 0, 0, 0);
;                 ob0 = __builtin_amdgcn_mfma_f32_32x32x16_bf16(v0, pfb, ob0, 0, 0, 0);
;                 ob1 = __builtin_amdgcn_mfma_f32_32x32x16_bf16(v1, pfb, ob1, 0, 0, 0);
;             }
.LBB0_426:
	v_sub_f32_e32 v112, v112, v188
	v_exp_f32_e32 v112, v112
	v_sub_f32_e32 v113, v113, v188
	v_exp_f32_e32 v113, v113
	v_sub_f32_e32 v114, v114, v188
	v_exp_f32_e32 v114, v114
	v_sub_f32_e32 v115, v115, v188
	v_exp_f32_e32 v115, v115
	v_sub_f32_e32 v116, v116, v188
	v_add_f32_e32 v181, 0, v112
	v_exp_f32_e32 v116, v116
	v_sub_f32_e32 v117, v117, v188
	v_add_f32_e32 v181, v113, v181
	v_exp_f32_e32 v117, v117
	v_sub_f32_e32 v118, v118, v188
	v_add_f32_e32 v181, v114, v181
	v_exp_f32_e32 v118, v118
	v_sub_f32_e32 v119, v119, v188
	v_add_f32_e32 v181, v115, v181
	v_exp_f32_e32 v119, v119
	v_sub_f32_e32 v120, v120, v188
	v_add_f32_e32 v181, v116, v181
	v_exp_f32_e32 v120, v120
	v_sub_f32_e32 v121, v121, v188
	v_add_f32_e32 v181, v117, v181
	v_exp_f32_e32 v121, v121
	v_sub_f32_e32 v122, v122, v188
	v_add_f32_e32 v181, v118, v181
	v_exp_f32_e32 v122, v122
	v_sub_f32_e32 v123, v123, v188
	v_add_f32_e32 v181, v119, v181
	v_exp_f32_e32 v123, v123
	v_sub_f32_e32 v124, v124, v188
	v_add_f32_e32 v181, v120, v181
	v_exp_f32_e32 v124, v124
	v_sub_f32_e32 v125, v125, v188
	v_add_f32_e32 v181, v121, v181
	v_exp_f32_e32 v125, v125
	v_sub_f32_e32 v126, v126, v188
	v_add_f32_e32 v181, v122, v181
	v_exp_f32_e32 v126, v126
	v_sub_f32_e32 v127, v127, v188
	v_add_f32_e32 v181, v123, v181
	v_exp_f32_e32 v127, v127
	v_sub_f32_e32 v80, v80, v188
	v_add_f32_e32 v181, v124, v181
	v_exp_f32_e32 v211, v80
	v_sub_f32_e32 v80, v81, v188
	v_add_f32_e32 v181, v125, v181
	v_exp_f32_e32 v212, v80
	v_sub_f32_e32 v81, v82, v188
	v_add_f32_e32 v80, v126, v181
	v_exp_f32_e32 v181, v81
	v_sub_f32_e32 v81, v83, v188
	v_add_f32_e32 v80, v127, v80
	v_exp_f32_e32 v213, v81
	v_sub_f32_e32 v81, v84, v188
	v_add_f32_e32 v80, v211, v80
	v_exp_f32_e32 v214, v81
	v_sub_f32_e32 v81, v85, v188
	v_add_f32_e32 v80, v212, v80
	v_exp_f32_e32 v215, v81
	v_sub_f32_e32 v81, v86, v188
	v_add_f32_e32 v80, v181, v80
	v_exp_f32_e32 v216, v81
	v_sub_f32_e32 v81, v87, v188
	v_add_f32_e32 v80, v213, v80
	v_exp_f32_e32 v217, v81
	v_sub_f32_e32 v81, v88, v188
	v_add_f32_e32 v80, v214, v80
	v_exp_f32_e32 v218, v81
	v_sub_f32_e32 v81, v89, v188
	v_add_f32_e32 v80, v215, v80
	v_exp_f32_e32 v220, v81
	v_add_f32_e32 v80, v216, v80
	v_add_f32_e32 v80, v217, v80
	v_add_f32_e32 v80, v218, v80
	v_add_f32_e32 v224, v220, v80
	v_sub_f32_e32 v80, v90, v188
	v_exp_f32_e32 v225, v80
	v_sub_f32_e32 v80, v91, v188
	v_exp_f32_e32 v226, v80
	v_sub_f32_e32 v80, v92, v188
	v_exp_f32_e32 v92, v80
	v_add_u32_e32 v80, s12, v178
	v_sub_f32_e32 v81, v96, v186
	v_add_u32_e32 v88, v80, v164
	v_exp_f32_e32 v184, v81
	v_sub_f32_e32 v81, v97, v186
	v_add_u32_e32 v182, 0x4800, v88
	v_add_u32_e32 v183, 0x6800, v88
	v_exp_f32_e32 v189, v81
	ds_read2_b64 v[80:83], v182 offset1:2
	ds_read2_b64 v[88:91], v183 offset0:32 offset1:34
	v_sub_f32_e32 v96, v99, v186
	v_sub_f32_e32 v84, v98, v186
	v_exp_f32_e32 v191, v96
	v_sub_f32_e32 v96, v100, v186
	v_exp_f32_e32 v190, v84
	v_cvt_pk_bf16_f32 v84, v112, v113
	v_cvt_pk_bf16_f32 v85, v114, v115
	v_cvt_pk_bf16_f32 v86, v116, v117
	v_cvt_pk_bf16_f32 v87, v118, v119
	v_exp_f32_e32 v192, v96
	v_sub_f32_e32 v96, v101, v186
	s_waitcnt lgkmcnt(1)
	v_mfma_f32_32x32x16_bf16 v[48:63], v[80:83], v[84:87], v[48:63]
	v_exp_f32_e32 v193, v96
	v_sub_f32_e32 v96, v102, v186
	v_exp_f32_e32 v194, v96
	v_sub_f32_e32 v96, v107, v186
	v_exp_f32_e32 v199, v96
	v_sub_f32_e32 v96, v108, v186
	v_exp_f32_e32 v204, v96
	s_waitcnt lgkmcnt(0)
	v_mfma_f32_32x32x16_bf16 v[32:47], v[88:91], v[84:87], v[32:47]
	v_sub_f32_e32 v84, v103, v186
	v_exp_f32_e32 v195, v84
	v_cvt_pk_bf16_f32 v84, v184, v189
	v_cvt_pk_bf16_f32 v85, v190, v191
	v_cvt_pk_bf16_f32 v86, v192, v193
	v_cvt_pk_bf16_f32 v87, v194, v195
	v_sub_f32_e32 v96, v109, v186
	v_exp_f32_e32 v205, v96
	v_mfma_f32_32x32x16_bf16 v[16:31], v[80:83], v[84:87], v[16:31]
	v_sub_f32_e32 v80, v93, v188
	v_exp_f32_e32 v93, v80
	v_sub_f32_e32 v80, v104, v186
	v_exp_f32_e32 v196, v80
	v_sub_f32_e32 v80, v105, v186
	v_exp_f32_e32 v197, v80
	ds_read2_b64 v[80:83], v182 offset0:4 offset1:6
	v_mfma_f32_32x32x16_bf16 v[0:15], v[88:91], v[84:87], v[0:15]
	ds_read2_b64 v[88:91], v183 offset0:36 offset1:38
	v_sub_f32_e32 v84, v106, v186
	v_exp_f32_e32 v198, v84
	v_cvt_pk_bf16_f32 v84, v120, v121
	v_cvt_pk_bf16_f32 v85, v122, v123
	v_cvt_pk_bf16_f32 v86, v124, v125
	v_cvt_pk_bf16_f32 v87, v126, v127
	v_sub_f32_e32 v96, v110, v186
	v_exp_f32_e32 v206, v96
	s_waitcnt lgkmcnt(1)
	v_mfma_f32_32x32x16_bf16 v[48:63], v[80:83], v[84:87], v[48:63]
	v_sub_f32_e32 v64, v64, v186
	v_exp_f32_e32 v208, v64
	v_sub_f32_e32 v64, v65, v186
	v_exp_f32_e32 v209, v64
	v_sub_f32_e32 v64, v66, v186
	v_exp_f32_e32 v210, v64
	v_sub_f32_e32 v64, v67, v186
	s_waitcnt lgkmcnt(0)
; #define LAS __attribute__((address_space(3)))
; template <int DK, bool IS_A>
; __device__ __forceinline__ void attn_unit(const Params& P, int l, LAS unsigned char* lds, int b, int grp, int qtok0, int nkeys) {
;     ...
;             __builtin_amdgcn_s_setprio(1);
; #pragma unroll
;             for (int i = 0; i < DK / 16; ++i)
; #pragma unroll
;                 for (int jj = 0; jj < 2; ++jj) {
;                     const bf16x8 kf = *(const LAS bf16x8*)(kb + jj * 32 * AK_PITCH + i * 32);
;                     pa[jj] = __builtin_amdgcn_mfma_f32_32x32x16_bf16(kf, qa[i], pa[jj], 0, 0, 0);
;                     pb[jj] = __builtin_amdgcn_mfma_f32_32x32x16_bf16(kf, qb[i], pb[jj], 0, 0, 0);
;                 }
;             __builtin_amdgcn_s_setprio(0);
;     ...
;             AT_SOFTMAX(pa, ma, la, oa0, oa1);
;             AT_SOFTMAX(pb, mb, lb_, ob0, ob1);
;     ...
; #pragma unroll
;             for (int ks = 0; ks < 4; ++ks) {
;                 const int o8 = 8 * (ks & 1);
;                 u32x4 w; const f32x16& xa = pa[ks >> 1]; const f32x16& xb = pb[ks >> 1];
;                 w.x = pk2(xa[o8], xa[o8 + 1]); w.y = pk2(xa[o8 + 2], xa[o8 + 3]); w.z = pk2(xa[o8 + 4], xa[o8 + 5]); w.w = pk2(xa[o8 + 6], xa[o8 + 7]);
;                 const bf16x8 pfa = __builtin_bit_cast(bf16x8, w);
;                 w.x = pk2(xb[o8], xb[o8 + 1]); w.y = pk2(xb[o8 + 2], xb[o8 + 3]); w.z = pk2(xb[o8 + 4], xb[o8 + 5]); w.w = pk2(xb[o8 + 6], xb[o8 + 7]);
;                 const bf16x8 pfb = __builtin_bit_cast(bf16x8, w);
;                 const u32x2 a0 = *(const LAS u32x2*)(vb + ks * 32), a1 = *(const LAS u32x2*)(vb + ks * 32 + 16);
;                 const u32x2 c0 = *(const LAS u32x2*)(vb + 32 * AV_PITCH + ks * 32), c1 = *(const LAS u32x2*)(vb + 32 * AV_PITCH + ks * 32 + 16);
;                 const bf16x8 v0 = __builtin_bit_cast(bf16x8, ((u32x4){a0.x, a0.y, a1.x, a1.y})), v1 = __builtin_bit_cast(bf16x8, ((u32x4){c0.x, c0.y, c1.x, c1.y}));
;                 oa0 = __builtin_amdgcn_mfma_f32_32x32x16_bf16(v0, pfa, oa0, 0, 0, 0);
;                 oa1 = __builtin_amdgcn_mfma_f32_32x32x16_bf16(v1, pfa, oa1, 0, 0, 0);
;                 ob0 = __builtin_amdgcn_mfma_f32_32x32x16_bf16(v0, pfb, ob0, 0, 0, 0);
;                 ob1 = __builtin_amdgcn_mfma_f32_32x32x16_bf16(v1, pfb, ob1, 0, 0, 0);
;             }
	v_mfma_f32_32x32x16_bf16 v[32:47], v[88:91], v[84:87], v[32:47]
	v_sub_f32_e32 v84, v111, v186
	v_exp_f32_e32 v207, v84
	v_cvt_pk_bf16_f32 v84, v196, v197
	v_cvt_pk_bf16_f32 v85, v198, v199
	v_cvt_pk_bf16_f32 v86, v204, v205
	v_cvt_pk_bf16_f32 v87, v206, v207
	s_nop 1
	v_mfma_f32_32x32x16_bf16 v[16:31], v[80:83], v[84:87], v[16:31]
	v_sub_f32_e32 v80, v94, v188
	v_exp_f32_e32 v94, v80
	ds_read2_b64 v[80:83], v182 offset0:8 offset1:10
	v_mfma_f32_32x32x16_bf16 v[0:15], v[88:91], v[84:87], v[0:15]
	ds_read2_b64 v[88:91], v183 offset0:40 offset1:42
	v_cvt_pk_bf16_f32 v84, v211, v212
	v_exp_f32_e32 v211, v64
	v_sub_f32_e32 v64, v68, v186
	v_exp_f32_e32 v212, v64
	v_sub_f32_e32 v64, v69, v186
	v_cvt_pk_bf16_f32 v85, v181, v213
	v_exp_f32_e32 v213, v64
	v_sub_f32_e32 v64, v70, v186
	v_cvt_pk_bf16_f32 v86, v214, v215
	v_exp_f32_e32 v214, v64
	v_sub_f32_e32 v64, v71, v186
	v_exp_f32_e32 v215, v64
	v_cvt_pk_bf16_f32 v87, v216, v217
	v_sub_f32_e32 v68, v95, v188
	v_cvt_pk_bf16_f32 v64, v208, v209
	s_waitcnt lgkmcnt(1)
	v_mfma_f32_32x32x16_bf16 v[48:63], v[80:83], v[84:87], v[48:63]
	v_cvt_pk_bf16_f32 v65, v210, v211
	v_cvt_pk_bf16_f32 v66, v212, v213
	v_cvt_pk_bf16_f32 v67, v214, v215
	s_waitcnt lgkmcnt(0)
	v_mfma_f32_32x32x16_bf16 v[32:47], v[88:91], v[84:87], v[32:47]
	v_exp_f32_e32 v84, v68
	v_sub_f32_e32 v68, v72, v186
	v_exp_f32_e32 v216, v68
	v_sub_f32_e32 v68, v73, v186
	v_exp_f32_e32 v217, v68
	ds_read2_b64 v[68:71], v182 offset0:12 offset1:14
	v_sub_f32_e32 v72, v75, v186
	v_mfma_f32_32x32x16_bf16 v[16:31], v[80:83], v[64:67], v[16:31]
	ds_read2_b64 v[80:83], v183 offset0:44 offset1:46
	v_exp_f32_e32 v222, v72
	v_sub_f32_e32 v72, v76, v186
	v_exp_f32_e32 v223, v72
	v_sub_f32_e32 v72, v77, v186
	v_mfma_f32_32x32x16_bf16 v[0:15], v[88:91], v[64:67], v[0:15]
	v_sub_f32_e32 v64, v74, v186
	v_exp_f32_e32 v219, v64
	v_cvt_pk_bf16_f32 v64, v218, v220
	v_cvt_pk_bf16_f32 v65, v225, v226
	v_cvt_pk_bf16_f32 v66, v92, v93
	v_cvt_pk_bf16_f32 v67, v94, v84
	v_exp_f32_e32 v218, v72
	v_sub_f32_e32 v72, v78, v186
	s_waitcnt lgkmcnt(1)
	v_mfma_f32_32x32x16_bf16 v[48:63], v[68:71], v[64:67], v[48:63]
	v_exp_f32_e32 v220, v72
	s_waitcnt lgkmcnt(0)
	v_mfma_f32_32x32x16_bf16 v[32:47], v[80:83], v[64:67], v[32:47]
	v_sub_f32_e32 v64, v79, v186
	v_exp_f32_e32 v221, v64
	v_cvt_pk_bf16_f32 v64, v216, v217
	v_cvt_pk_bf16_f32 v65, v219, v222
	v_cvt_pk_bf16_f32 v66, v223, v218
	v_cvt_pk_bf16_f32 v67, v220, v221
	s_nop 1
	v_mfma_f32_32x32x16_bf16 v[16:31], v[68:71], v[64:67], v[16:31]
	v_add_f32_e32 v68, v225, v224
	v_add_f32_e32 v68, v226, v68
	v_add_f32_e32 v68, v92, v68
	v_add_f32_e32 v68, v93, v68
	v_add_f32_e32 v68, v94, v68
	v_add_f32_e32 v68, v84, v68
	v_add_f32_e32 v185, v185, v68
	v_mfma_f32_32x32x16_bf16 v[0:15], v[80:83], v[64:67], v[0:15]
	s_setprio 1
	ds_read_b128 v[64:67], v187 offset:9216
	ds_read_b128 v[224:227], v187 offset:9248
	s_waitcnt lgkmcnt(1)
	v_mfma_f32_32x32x16_bf16 v[112:127], v[64:67], v[138:141], 0
	v_mfma_f32_32x32x16_bf16 v[96:111], v[64:67], v[146:149], 0
	ds_read_b128 v[64:67], v187 offset:13824
	s_waitcnt lgkmcnt(1)
	v_mfma_f32_32x32x16_bf16 v[112:127], v[224:227], v[142:145], v[112:127]
	v_mfma_f32_32x32x16_bf16 v[96:111], v[224:227], v[150:153], v[96:111]
	ds_read_b128 v[224:227], v187 offset:13856
	s_waitcnt lgkmcnt(1)
	v_mfma_f32_32x32x16_bf16 v[80:95], v[64:67], v[138:141], 0
	v_mfma_f32_32x32x16_bf16 v[64:79], v[64:67], v[146:149], 0
	s_waitcnt lgkmcnt(0)
	v_mfma_f32_32x32x16_bf16 v[80:95], v[224:227], v[142:145], v[80:95]
	v_mfma_f32_32x32x16_bf16 v[64:79], v[224:227], v[150:153], v[64:79]
	s_setprio 0
	s_nop 9
	v_max_f32_e32 v181, v80, v80
	v_max_f32_e32 v187, v112, v112
	v_max_f32_e32 v181, v187, v181
	v_max3_f32 v187, v81, v114, v82
	v_max3_f32 v181, v181, v113, v115
	v_max3_f32 v187, v187, v116, v84
	v_max3_f32 v181, v181, v83, v117
	v_max3_f32 v187, v187, v118, v86
	v_max3_f32 v181, v181, v85, v119
	v_max3_f32 v187, v187, v120, v88
	v_max3_f32 v181, v181, v87, v121
	v_max3_f32 v187, v187, v122, v90
	v_max3_f32 v181, v181, v89, v123
	v_max3_f32 v187, v187, v124, v92
	v_max3_f32 v181, v181, v91, v125
	v_max3_f32 v187, v187, v126, v94
	v_max3_f32 v181, v181, v93, v127
	v_max3_f32 v181, v181, v95, v187
	ds_bpermute_b32 v187, v163, v181
	s_waitcnt lgkmcnt(0)
	v_max3_f32 v181, v188, v181, v187
	v_add_f32_e32 v187, 0x41000000, v188
	v_cmp_gt_f32_e32 vcc, v181, v187
	s_cbranch_vccz .LBB0_428
	v_sub_f32_e32 v187, v188, v181
	v_exp_f32_e32 v188, v187
	s_nop 0
	v_pk_mul_f32 v[62:63], v[62:63], v[188:189] op_sel_hi:[1,0]
	v_pk_mul_f32 v[60:61], v[60:61], v[188:189] op_sel_hi:[1,0]
	v_pk_mul_f32 v[58:59], v[58:59], v[188:189] op_sel_hi:[1,0]
	v_pk_mul_f32 v[56:57], v[56:57], v[188:189] op_sel_hi:[1,0]
	v_pk_mul_f32 v[54:55], v[54:55], v[188:189] op_sel_hi:[1,0]
	v_pk_mul_f32 v[52:53], v[52:53], v[188:189] op_sel_hi:[1,0]
	v_pk_mul_f32 v[50:51], v[50:51], v[188:189] op_sel_hi:[1,0]
	v_pk_mul_f32 v[48:49], v[48:49], v[188:189] op_sel_hi:[1,0]
	v_pk_mul_f32 v[46:47], v[46:47], v[188:189] op_sel_hi:[1,0]
	v_pk_mul_f32 v[44:45], v[44:45], v[188:189] op_sel_hi:[1,0]
	v_pk_mul_f32 v[42:43], v[42:43], v[188:189] op_sel_hi:[1,0]
	v_pk_mul_f32 v[40:41], v[40:41], v[188:189] op_sel_hi:[1,0]
	v_pk_mul_f32 v[38:39], v[38:39], v[188:189] op_sel_hi:[1,0]
	v_pk_mul_f32 v[36:37], v[36:37], v[188:189] op_sel_hi:[1,0]
	v_pk_mul_f32 v[34:35], v[34:35], v[188:189] op_sel_hi:[1,0]
	v_pk_mul_f32 v[32:33], v[32:33], v[188:189] op_sel_hi:[1,0]
	v_mul_f32_e32 v185, v185, v188
	s_branch .LBB0_429

; template <int DK, bool IS_A>
; __device__ __forceinline__ void attn_unit(const Params& P, int l, LAS unsigned char* lds, int b, int grp, int qtok0, int nkeys) {
;     ...
;             AT_SOFTMAX(pa, ma, la, oa0, oa1);
;             AT_SOFTMAX(pb, mb, lb_, ob0, ob1);
.LBB0_429:
	v_add_f32_e32 v184, 0, v184
	v_add_f32_e32 v184, v189, v184
	v_add_f32_e32 v184, v190, v184
	v_add_f32_e32 v184, v191, v184
	v_add_f32_e32 v184, v192, v184
	v_add_f32_e32 v184, v193, v184
	v_add_f32_e32 v184, v194, v184
	v_add_f32_e32 v184, v195, v184
	v_add_f32_e32 v184, v196, v184
	v_add_f32_e32 v184, v197, v184
	v_add_f32_e32 v184, v198, v184
	v_add_f32_e32 v184, v199, v184
	v_add_f32_e32 v184, v204, v184
	v_add_f32_e32 v184, v205, v184
	v_add_f32_e32 v184, v206, v184
	v_add_f32_e32 v184, v207, v184
	v_add_f32_e32 v184, v208, v184
	v_add_f32_e32 v184, v209, v184
	v_max_f32_e32 v187, v64, v64
	v_max_f32_e32 v188, v96, v96
	v_add_f32_e32 v184, v210, v184
	v_max_f32_e32 v187, v188, v187
	v_add_f32_e32 v184, v211, v184
	v_max3_f32 v188, v65, v98, v66
	v_max3_f32 v187, v187, v97, v99
	v_add_f32_e32 v184, v212, v184
	v_max3_f32 v188, v188, v100, v68
	v_max3_f32 v187, v187, v67, v101
	v_add_f32_e32 v184, v213, v184
	v_max3_f32 v188, v188, v102, v70
	v_max3_f32 v187, v187, v69, v103
	v_add_f32_e32 v184, v214, v184
	v_max3_f32 v188, v188, v104, v72
	v_max3_f32 v187, v187, v71, v105
	v_add_f32_e32 v184, v215, v184
	v_max3_f32 v188, v188, v106, v74
	v_max3_f32 v187, v187, v73, v107
	v_add_f32_e32 v184, v216, v184
	v_max3_f32 v188, v188, v108, v76
	v_max3_f32 v187, v187, v75, v109
	v_add_f32_e32 v184, v217, v184
	v_max3_f32 v188, v188, v110, v78
	v_max3_f32 v187, v187, v77, v111
	v_add_f32_e32 v184, v219, v184
	v_max3_f32 v187, v187, v79, v188
	v_add_f32_e32 v184, v222, v184
	ds_bpermute_b32 v188, v163, v187
	v_add_f32_e32 v184, v223, v184
	v_add_f32_e32 v184, v218, v184
	v_add_f32_e32 v184, v220, v184
	v_add_f32_e32 v184, v221, v184
	v_add_f32_e32 v180, v180, v184
	s_waitcnt lgkmcnt(0)
	v_max3_f32 v184, v186, v187, v188
	v_add_f32_e32 v188, 0x41000000, v186
	v_cmp_gt_f32_e32 vcc, v184, v188
	s_cbranch_vccz .LBB0_431
	v_sub_f32_e32 v186, v186, v184
	v_exp_f32_e32 v186, v186
	s_nop 0
	v_pk_mul_f32 v[30:31], v[30:31], v[186:187] op_sel_hi:[1,0]
	v_pk_mul_f32 v[28:29], v[28:29], v[186:187] op_sel_hi:[1,0]
	v_pk_mul_f32 v[26:27], v[26:27], v[186:187] op_sel_hi:[1,0]
	v_pk_mul_f32 v[24:25], v[24:25], v[186:187] op_sel_hi:[1,0]
	v_pk_mul_f32 v[22:23], v[22:23], v[186:187] op_sel_hi:[1,0]
	v_pk_mul_f32 v[20:21], v[20:21], v[186:187] op_sel_hi:[1,0]
	v_pk_mul_f32 v[18:19], v[18:19], v[186:187] op_sel_hi:[1,0]
	v_pk_mul_f32 v[16:17], v[16:17], v[186:187] op_sel_hi:[1,0]
	v_pk_mul_f32 v[14:15], v[14:15], v[186:187] op_sel_hi:[1,0]
	v_pk_mul_f32 v[12:13], v[12:13], v[186:187] op_sel_hi:[1,0]
	v_pk_mul_f32 v[10:11], v[10:11], v[186:187] op_sel_hi:[1,0]
	v_pk_mul_f32 v[8:9], v[8:9], v[186:187] op_sel_hi:[1,0]
	v_pk_mul_f32 v[6:7], v[6:7], v[186:187] op_sel_hi:[1,0]
	v_pk_mul_f32 v[4:5], v[4:5], v[186:187] op_sel_hi:[1,0]
	v_pk_mul_f32 v[2:3], v[2:3], v[186:187] op_sel_hi:[1,0]
	v_pk_mul_f32 v[0:1], v[0:1], v[186:187] op_sel_hi:[1,0]
	v_mul_f32_e32 v180, v180, v186
	s_branch .LBB0_432

; #define LAS __attribute__((address_space(3)))
; template <int DK, bool IS_A>
; __device__ __forceinline__ void attn_unit(const Params& P, int l, LAS unsigned char* lds, int b, int grp, int qtok0, int nkeys) {
;     ...
;         for (int h = 0; h < 2; ++h) {
;             const LAS unsigned char* kb = lds + buf * A_BUF + kfo + h * 64 * AK_PITCH;
;             const LAS unsigned char* vb = lds + buf * A_BUF + vfo + h * 128;
;             f32x16 pa[2], pb[2];
; #pragma unroll
;             for (int jj = 0; jj < 2; ++jj)
; #pragma unroll
;                 for (int r = 0; r < 16; ++r) { pa[jj][r] = 0.f; pb[jj][r] = 0.f; }
;             __builtin_amdgcn_s_setprio(1);
; #pragma unroll
;             for (int i = 0; i < DK / 16; ++i)
; #pragma unroll
;                 for (int jj = 0; jj < 2; ++jj) {
;                     const bf16x8 kf = *(const LAS bf16x8*)(kb + jj * 32 * AK_PITCH + i * 32);
;                     pa[jj] = __builtin_amdgcn_mfma_f32_32x32x16_bf16(kf, qa[i], pa[jj], 0, 0, 0);
;                     pb[jj] = __builtin_amdgcn_mfma_f32_32x32x16_bf16(kf, qb[i], pb[jj], 0, 0, 0);
;                 }
;             __builtin_amdgcn_s_setprio(0);
.LBB0_445:
	s_mov_b32 s12, s100
	v_add_u32_e32 v64, s12, v178
	v_add_u32_e32 v199, v64, v192
	s_setprio 1
	ds_read_b128 v[64:67], v199
	ds_read_b128 v[204:207], v199 offset:32
	s_waitcnt lgkmcnt(1)
	v_mfma_f32_32x32x16_bf16 v[112:127], v[64:67], v[142:145], 0
	v_mfma_f32_32x32x16_bf16 v[96:111], v[64:67], v[146:149], 0
	ds_read_b128 v[64:67], v199 offset:4608
	s_waitcnt lgkmcnt(1)
	v_mfma_f32_32x32x16_bf16 v[112:127], v[204:207], v[154:157], v[112:127]
	v_mfma_f32_32x32x16_bf16 v[96:111], v[204:207], v[162:165], v[96:111]
	ds_read_b128 v[204:207], v199 offset:4640
	s_waitcnt lgkmcnt(1)
	v_mfma_f32_32x32x16_bf16 v[80:95], v[64:67], v[142:145], 0
	v_mfma_f32_32x32x16_bf16 v[64:79], v[64:67], v[146:149], 0
	s_waitcnt lgkmcnt(0)
	v_mfma_f32_32x32x16_bf16 v[80:95], v[204:207], v[154:157], v[80:95]
	v_mfma_f32_32x32x16_bf16 v[64:79], v[204:207], v[162:165], v[64:79]
	ds_read_b128 v[204:207], v199 offset:64
	s_waitcnt lgkmcnt(0)
	v_mfma_f32_32x32x16_bf16 v[112:127], v[204:207], v[158:161], v[112:127]
	v_mfma_f32_32x32x16_bf16 v[96:111], v[204:207], v[170:173], v[96:111]
	ds_read_b128 v[204:207], v199 offset:4672
	s_waitcnt lgkmcnt(0)
	v_mfma_f32_32x32x16_bf16 v[80:95], v[204:207], v[158:161], v[80:95]
	v_mfma_f32_32x32x16_bf16 v[64:79], v[204:207], v[170:173], v[64:79]
	ds_read_b128 v[204:207], v199 offset:96
	s_waitcnt lgkmcnt(0)
	v_mfma_f32_32x32x16_bf16 v[112:127], v[204:207], v[166:169], v[112:127]
	v_mfma_f32_32x32x16_bf16 v[96:111], v[204:207], v[174:177], v[96:111]
	ds_read_b128 v[204:207], v199 offset:4704
	s_waitcnt lgkmcnt(0)
	v_mfma_f32_32x32x16_bf16 v[80:95], v[204:207], v[166:169], v[80:95]
	v_mfma_f32_32x32x16_bf16 v[64:79], v[204:207], v[174:177], v[64:79]
	s_setprio 0
	s_nop 9
	v_max_f32_e32 v185, v80, v80
	v_max_f32_e32 v187, v112, v112
	v_max_f32_e32 v185, v187, v185
	v_max3_f32 v187, v81, v114, v82
	v_max3_f32 v185, v185, v113, v115
	v_max3_f32 v187, v187, v116, v84
	v_max3_f32 v185, v185, v83, v117
	v_max3_f32 v187, v187, v118, v86
	v_max3_f32 v185, v185, v85, v119
	v_max3_f32 v187, v187, v120, v88
	v_max3_f32 v185, v185, v87, v121
	v_max3_f32 v187, v187, v122, v90
	v_max3_f32 v185, v185, v89, v123
	v_max3_f32 v187, v187, v124, v92
	v_max3_f32 v185, v185, v91, v125
	v_max3_f32 v187, v187, v126, v94
	v_max3_f32 v185, v185, v93, v127
	v_max3_f32 v185, v185, v95, v187
	ds_bpermute_b32 v187, v181, v185
	s_waitcnt lgkmcnt(0)
	v_max3_f32 v205, v184, v185, v187
	v_add_f32_e32 v187, 0x41000000, v184
	v_cmp_gt_f32_e32 vcc, v205, v187
	s_cbranch_vccz .LBB0_447
	v_sub_f32_e32 v184, v184, v205
	v_exp_f32_e32 v184, v184
	s_nop 0
	v_pk_mul_f32 v[62:63], v[62:63], v[184:185] op_sel_hi:[1,0]
	v_pk_mul_f32 v[60:61], v[60:61], v[184:185] op_sel_hi:[1,0]
	v_pk_mul_f32 v[58:59], v[58:59], v[184:185] op_sel_hi:[1,0]
	v_pk_mul_f32 v[56:57], v[56:57], v[184:185] op_sel_hi:[1,0]
	v_pk_mul_f32 v[54:55], v[54:55], v[184:185] op_sel_hi:[1,0]
	v_pk_mul_f32 v[52:53], v[52:53], v[184:185] op_sel_hi:[1,0]
	v_pk_mul_f32 v[50:51], v[50:51], v[184:185] op_sel_hi:[1,0]
	v_pk_mul_f32 v[48:49], v[48:49], v[184:185] op_sel_hi:[1,0]
	v_pk_mul_f32 v[46:47], v[46:47], v[184:185] op_sel_hi:[1,0]
	v_pk_mul_f32 v[44:45], v[44:45], v[184:185] op_sel_hi:[1,0]
	v_pk_mul_f32 v[42:43], v[42:43], v[184:185] op_sel_hi:[1,0]
	v_pk_mul_f32 v[40:41], v[40:41], v[184:185] op_sel_hi:[1,0]
	v_pk_mul_f32 v[38:39], v[38:39], v[184:185] op_sel_hi:[1,0]
	v_pk_mul_f32 v[36:37], v[36:37], v[184:185] op_sel_hi:[1,0]
	v_pk_mul_f32 v[34:35], v[34:35], v[184:185] op_sel_hi:[1,0]
	v_pk_mul_f32 v[32:33], v[32:33], v[184:185] op_sel_hi:[1,0]
	v_mul_f32_e32 v198, v198, v184
	s_branch .LBB0_448

; template <int DK, bool IS_A>
; __device__ __forceinline__ void attn_unit(const Params& P, int l, LAS unsigned char* lds, int b, int grp, int qtok0, int nkeys) {
;     ...
;             AT_SOFTMAX(pa, ma, la, oa0, oa1);
;             AT_SOFTMAX(pb, mb, lb_, ob0, ob1);
.LBB0_448:
	v_max_f32_e32 v184, v64, v64
	v_max_f32_e32 v185, v96, v96
	v_max_f32_e32 v184, v185, v184
	v_max3_f32 v185, v65, v98, v66
	v_max3_f32 v184, v184, v97, v99
	v_max3_f32 v185, v185, v100, v68
	v_max3_f32 v184, v184, v67, v101
	v_max3_f32 v185, v185, v102, v70
	v_max3_f32 v184, v184, v69, v103
	v_max3_f32 v185, v185, v104, v72
	v_max3_f32 v184, v184, v71, v105
	v_max3_f32 v185, v185, v106, v74
	v_max3_f32 v184, v184, v73, v107
	v_max3_f32 v185, v185, v108, v76
	v_max3_f32 v184, v184, v75, v109
	v_max3_f32 v185, v185, v110, v78
	v_max3_f32 v184, v184, v77, v111
	v_max3_f32 v184, v184, v79, v185
	ds_bpermute_b32 v185, v181, v184
	s_waitcnt lgkmcnt(0)
	v_max3_f32 v204, v193, v184, v185
	v_add_f32_e32 v185, 0x41000000, v193
	v_cmp_gt_f32_e32 vcc, v204, v185
	s_cbranch_vccz .LBB0_450
	v_sub_f32_e32 v184, v193, v204
	v_exp_f32_e32 v184, v184
	s_nop 0
	v_pk_mul_f32 v[30:31], v[30:31], v[184:185] op_sel_hi:[1,0]
	v_pk_mul_f32 v[28:29], v[28:29], v[184:185] op_sel_hi:[1,0]
	v_pk_mul_f32 v[26:27], v[26:27], v[184:185] op_sel_hi:[1,0]
	v_pk_mul_f32 v[24:25], v[24:25], v[184:185] op_sel_hi:[1,0]
	v_pk_mul_f32 v[22:23], v[22:23], v[184:185] op_sel_hi:[1,0]
	v_pk_mul_f32 v[20:21], v[20:21], v[184:185] op_sel_hi:[1,0]
	v_pk_mul_f32 v[18:19], v[18:19], v[184:185] op_sel_hi:[1,0]
	v_pk_mul_f32 v[16:17], v[16:17], v[184:185] op_sel_hi:[1,0]
	v_pk_mul_f32 v[14:15], v[14:15], v[184:185] op_sel_hi:[1,0]
	v_pk_mul_f32 v[12:13], v[12:13], v[184:185] op_sel_hi:[1,0]
	v_pk_mul_f32 v[10:11], v[10:11], v[184:185] op_sel_hi:[1,0]
	v_pk_mul_f32 v[8:9], v[8:9], v[184:185] op_sel_hi:[1,0]
	v_pk_mul_f32 v[6:7], v[6:7], v[184:185] op_sel_hi:[1,0]
	v_pk_mul_f32 v[4:5], v[4:5], v[184:185] op_sel_hi:[1,0]
	v_pk_mul_f32 v[2:3], v[2:3], v[184:185] op_sel_hi:[1,0]
	v_pk_mul_f32 v[0:1], v[0:1], v[184:185] op_sel_hi:[1,0]
	v_mul_f32_e32 v183, v183, v184
	s_branch .LBB0_451

; #define LAS __attribute__((address_space(3)))
; __device__ __forceinline__ unsigned pk2(float lo, float hi) { f32x2_t v = {lo, hi}; bf16x2_t b = __builtin_convertvector(v, bf16x2_t); return __builtin_bit_cast(unsigned, b); }
; template <int DK, bool IS_A>
; __device__ __forceinline__ void attn_unit(const Params& P, int l, LAS unsigned char* lds, int b, int grp, int qtok0, int nkeys) {
;     ...
;             AT_SOFTMAX(pa, ma, la, oa0, oa1);
;             AT_SOFTMAX(pb, mb, lb_, ob0, ob1);
;     ...
; #pragma unroll
;             for (int ks = 0; ks < 4; ++ks) {
;                 const int o8 = 8 * (ks & 1);
;                 u32x4 w; const f32x16& xa = pa[ks >> 1]; const f32x16& xb = pb[ks >> 1];
;                 w.x = pk2(xa[o8], xa[o8 + 1]); w.y = pk2(xa[o8 + 2], xa[o8 + 3]); w.z = pk2(xa[o8 + 4], xa[o8 + 5]); w.w = pk2(xa[o8 + 6], xa[o8 + 7]);
;                 const bf16x8 pfa = __builtin_bit_cast(bf16x8, w);
;                 w.x = pk2(xb[o8], xb[o8 + 1]); w.y = pk2(xb[o8 + 2], xb[o8 + 3]); w.z = pk2(xb[o8 + 4], xb[o8 + 5]); w.w = pk2(xb[o8 + 6], xb[o8 + 7]);
;                 const bf16x8 pfb = __builtin_bit_cast(bf16x8, w);
;                 const u32x2 a0 = *(const LAS u32x2*)(vb + ks * 32), a1 = *(const LAS u32x2*)(vb + ks * 32 + 16);
;                 const u32x2 c0 = *(const LAS u32x2*)(vb + 32 * AV_PITCH + ks * 32), c1 = *(const LAS u32x2*)(vb + 32 * AV_PITCH + ks * 32 + 16);
;                 const bf16x8 v0 = __builtin_bit_cast(bf16x8, ((u32x4){a0.x, a0.y, a1.x, a1.y})), v1 = __builtin_bit_cast(bf16x8, ((u32x4){c0.x, c0.y, c1.x, c1.y}));
;                 oa0 = __builtin_amdgcn_mfma_f32_32x32x16_bf16(v0, pfa, oa0, 0, 0, 0);
;                 oa1 = __builtin_amdgcn_mfma_f32_32x32x16_bf16(v1, pfa, oa1, 0, 0, 0);
;                 ob0 = __builtin_amdgcn_mfma_f32_32x32x16_bf16(v0, pfb, ob0, 0, 0, 0);
;                 ob1 = __builtin_amdgcn_mfma_f32_32x32x16_bf16(v1, pfb, ob1, 0, 0, 0);
;             }
.LBB0_451:
	v_sub_f32_e32 v112, v112, v205
	v_exp_f32_e32 v112, v112
	v_sub_f32_e32 v113, v113, v205
	v_exp_f32_e32 v113, v113
	v_sub_f32_e32 v114, v114, v205
	v_exp_f32_e32 v114, v114
	v_sub_f32_e32 v115, v115, v205
	v_exp_f32_e32 v115, v115
	v_sub_f32_e32 v116, v116, v205
	v_add_f32_e32 v184, 0, v112
	v_exp_f32_e32 v116, v116
	v_sub_f32_e32 v117, v117, v205
	v_add_f32_e32 v184, v113, v184
	v_exp_f32_e32 v117, v117
	v_sub_f32_e32 v118, v118, v205
	v_add_f32_e32 v184, v114, v184
	v_exp_f32_e32 v118, v118
	v_sub_f32_e32 v119, v119, v205
	v_add_f32_e32 v184, v115, v184
	v_exp_f32_e32 v119, v119
	v_sub_f32_e32 v120, v120, v205
	v_add_f32_e32 v184, v116, v184
	v_exp_f32_e32 v120, v120
	v_sub_f32_e32 v121, v121, v205
	v_add_f32_e32 v184, v117, v184
	v_exp_f32_e32 v121, v121
	v_sub_f32_e32 v122, v122, v205
	v_add_f32_e32 v184, v118, v184
	v_exp_f32_e32 v122, v122
	v_sub_f32_e32 v123, v123, v205
	v_add_f32_e32 v184, v119, v184
	v_exp_f32_e32 v123, v123
	v_sub_f32_e32 v124, v124, v205
	v_add_f32_e32 v184, v120, v184
	v_exp_f32_e32 v124, v124
	v_sub_f32_e32 v125, v125, v205
	v_add_f32_e32 v184, v121, v184
	v_exp_f32_e32 v125, v125
	v_sub_f32_e32 v126, v126, v205
	v_add_f32_e32 v184, v122, v184
	v_exp_f32_e32 v126, v126
	v_sub_f32_e32 v127, v127, v205
	v_add_f32_e32 v184, v123, v184
	v_exp_f32_e32 v127, v127
	v_sub_f32_e32 v80, v80, v205
	v_add_f32_e32 v184, v124, v184
	v_exp_f32_e32 v224, v80
	v_sub_f32_e32 v80, v81, v205
	v_add_f32_e32 v184, v125, v184
	v_exp_f32_e32 v225, v80
	v_sub_f32_e32 v81, v82, v205
	v_add_f32_e32 v80, v126, v184
	v_exp_f32_e32 v184, v81
	v_sub_f32_e32 v81, v83, v205
	v_add_f32_e32 v80, v127, v80
	v_exp_f32_e32 v226, v81
	v_sub_f32_e32 v81, v84, v205
	v_add_f32_e32 v80, v224, v80
	v_exp_f32_e32 v227, v81
	v_sub_f32_e32 v81, v85, v205
	v_add_f32_e32 v80, v225, v80
	v_exp_f32_e32 v228, v81
	v_sub_f32_e32 v81, v86, v205
	v_add_f32_e32 v80, v184, v80
	v_exp_f32_e32 v229, v81
	v_sub_f32_e32 v81, v87, v205
	v_add_f32_e32 v80, v226, v80
	v_exp_f32_e32 v230, v81
	v_sub_f32_e32 v81, v88, v205
	v_add_f32_e32 v80, v227, v80
	v_exp_f32_e32 v231, v81
	v_sub_f32_e32 v81, v89, v205
	v_add_f32_e32 v80, v228, v80
	v_exp_f32_e32 v233, v81
	v_add_f32_e32 v80, v229, v80
	v_add_f32_e32 v80, v230, v80
	v_add_f32_e32 v80, v231, v80
	v_add_f32_e32 v237, v233, v80
	v_sub_f32_e32 v80, v90, v205
	v_exp_f32_e32 v238, v80
	v_sub_f32_e32 v80, v91, v205
	v_exp_f32_e32 v239, v80
	v_sub_f32_e32 v80, v92, v205
	v_exp_f32_e32 v92, v80
	v_add_u32_e32 v80, s12, v182
	v_sub_f32_e32 v81, v96, v204
	v_add_u32_e32 v88, v80, v186
	v_exp_f32_e32 v193, v81
	v_sub_f32_e32 v81, v97, v204
	v_add_u32_e32 v185, 0x4800, v88
	v_add_u32_e32 v187, 0x6800, v88
	v_exp_f32_e32 v206, v81
	ds_read2_b64 v[80:83], v185 offset1:2
	ds_read2_b64 v[88:91], v187 offset0:32 offset1:34
	v_sub_f32_e32 v96, v99, v204
	v_sub_f32_e32 v84, v98, v204
	v_exp_f32_e32 v208, v96
	v_sub_f32_e32 v96, v100, v204
	v_exp_f32_e32 v207, v84
	v_cvt_pk_bf16_f32 v84, v112, v113
	v_cvt_pk_bf16_f32 v85, v114, v115
	v_cvt_pk_bf16_f32 v86, v116, v117
	v_cvt_pk_bf16_f32 v87, v118, v119
	v_exp_f32_e32 v209, v96
	v_sub_f32_e32 v96, v101, v204
	s_waitcnt lgkmcnt(1)
	v_mfma_f32_32x32x16_bf16 v[48:63], v[80:83], v[84:87], v[48:63]
	v_exp_f32_e32 v210, v96
	v_sub_f32_e32 v96, v102, v204
	v_exp_f32_e32 v211, v96
	v_sub_f32_e32 v96, v107, v204
	v_exp_f32_e32 v216, v96
	v_sub_f32_e32 v96, v108, v204
	v_exp_f32_e32 v217, v96
	s_waitcnt lgkmcnt(0)
	v_mfma_f32_32x32x16_bf16 v[32:47], v[88:91], v[84:87], v[32:47]
	v_sub_f32_e32 v84, v103, v204
	v_exp_f32_e32 v212, v84
	v_cvt_pk_bf16_f32 v84, v193, v206
	v_cvt_pk_bf16_f32 v85, v207, v208
	v_cvt_pk_bf16_f32 v86, v209, v210
	v_cvt_pk_bf16_f32 v87, v211, v212
	v_sub_f32_e32 v96, v109, v204
	v_exp_f32_e32 v218, v96
	v_mfma_f32_32x32x16_bf16 v[16:31], v[80:83], v[84:87], v[16:31]
	v_sub_f32_e32 v80, v93, v205
	v_exp_f32_e32 v93, v80
	v_sub_f32_e32 v80, v104, v204
	v_exp_f32_e32 v213, v80
	v_sub_f32_e32 v80, v105, v204
	v_exp_f32_e32 v214, v80
	ds_read2_b64 v[80:83], v185 offset0:4 offset1:6
	v_mfma_f32_32x32x16_bf16 v[0:15], v[88:91], v[84:87], v[0:15]
	ds_read2_b64 v[88:91], v187 offset0:36 offset1:38
	v_sub_f32_e32 v84, v106, v204
	v_exp_f32_e32 v215, v84
	v_cvt_pk_bf16_f32 v84, v120, v121
	v_cvt_pk_bf16_f32 v85, v122, v123
	v_cvt_pk_bf16_f32 v86, v124, v125
	v_cvt_pk_bf16_f32 v87, v126, v127
	v_sub_f32_e32 v96, v110, v204
	v_exp_f32_e32 v219, v96
	s_waitcnt lgkmcnt(1)
	v_mfma_f32_32x32x16_bf16 v[48:63], v[80:83], v[84:87], v[48:63]
	v_sub_f32_e32 v64, v64, v204
	v_exp_f32_e32 v221, v64
	v_sub_f32_e32 v64, v65, v204
	v_exp_f32_e32 v222, v64
	v_sub_f32_e32 v64, v66, v204
	v_exp_f32_e32 v223, v64
	v_sub_f32_e32 v64, v67, v204
	s_waitcnt lgkmcnt(0)
	v_mfma_f32_32x32x16_bf16 v[32:47], v[88:91], v[84:87], v[32:47]
	v_sub_f32_e32 v84, v111, v204
	v_exp_f32_e32 v220, v84
	v_cvt_pk_bf16_f32 v84, v213, v214
	v_cvt_pk_bf16_f32 v85, v215, v216
	v_cvt_pk_bf16_f32 v86, v217, v218
	v_cvt_pk_bf16_f32 v87, v219, v220
	s_nop 1
	v_mfma_f32_32x32x16_bf16 v[16:31], v[80:83], v[84:87], v[16:31]
	v_sub_f32_e32 v80, v94, v205
	v_exp_f32_e32 v94, v80
	ds_read2_b64 v[80:83], v185 offset0:8 offset1:10
	v_mfma_f32_32x32x16_bf16 v[0:15], v[88:91], v[84:87], v[0:15]
	ds_read2_b64 v[88:91], v187 offset0:40 offset1:42
	v_cvt_pk_bf16_f32 v84, v224, v225
	v_exp_f32_e32 v224, v64
	v_sub_f32_e32 v64, v68, v204
	v_exp_f32_e32 v225, v64
	v_sub_f32_e32 v64, v69, v204
	v_cvt_pk_bf16_f32 v85, v184, v226
	v_exp_f32_e32 v226, v64
	v_sub_f32_e32 v64, v70, v204
	v_cvt_pk_bf16_f32 v86, v227, v228
	v_exp_f32_e32 v227, v64
	v_sub_f32_e32 v64, v71, v204
	v_exp_f32_e32 v228, v64
	v_cvt_pk_bf16_f32 v87, v229, v230
	v_sub_f32_e32 v68, v95, v205
	v_cvt_pk_bf16_f32 v64, v221, v222
	s_waitcnt lgkmcnt(1)
; #define LAS __attribute__((address_space(3)))
; template <int DK, bool IS_A>
; __device__ __forceinline__ void attn_unit(const Params& P, int l, LAS unsigned char* lds, int b, int grp, int qtok0, int nkeys) {
;     ...
;             __builtin_amdgcn_s_setprio(1);
; #pragma unroll
;             for (int i = 0; i < DK / 16; ++i)
; #pragma unroll
;                 for (int jj = 0; jj < 2; ++jj) {
;                     const bf16x8 kf = *(const LAS bf16x8*)(kb + jj * 32 * AK_PITCH + i * 32);
;                     pa[jj] = __builtin_amdgcn_mfma_f32_32x32x16_bf16(kf, qa[i], pa[jj], 0, 0, 0);
;                     pb[jj] = __builtin_amdgcn_mfma_f32_32x32x16_bf16(kf, qb[i], pb[jj], 0, 0, 0);
;                 }
;             __builtin_amdgcn_s_setprio(0);
;     ...
;             AT_SOFTMAX(pa, ma, la, oa0, oa1);
;             AT_SOFTMAX(pb, mb, lb_, ob0, ob1);
;     ...
; #pragma unroll
;             for (int ks = 0; ks < 4; ++ks) {
;                 const int o8 = 8 * (ks & 1);
;                 u32x4 w; const f32x16& xa = pa[ks >> 1]; const f32x16& xb = pb[ks >> 1];
;                 w.x = pk2(xa[o8], xa[o8 + 1]); w.y = pk2(xa[o8 + 2], xa[o8 + 3]); w.z = pk2(xa[o8 + 4], xa[o8 + 5]); w.w = pk2(xa[o8 + 6], xa[o8 + 7]);
;                 const bf16x8 pfa = __builtin_bit_cast(bf16x8, w);
;                 w.x = pk2(xb[o8], xb[o8 + 1]); w.y = pk2(xb[o8 + 2], xb[o8 + 3]); w.z = pk2(xb[o8 + 4], xb[o8 + 5]); w.w = pk2(xb[o8 + 6], xb[o8 + 7]);
;                 const bf16x8 pfb = __builtin_bit_cast(bf16x8, w);
;                 const u32x2 a0 = *(const LAS u32x2*)(vb + ks * 32), a1 = *(const LAS u32x2*)(vb + ks * 32 + 16);
;                 const u32x2 c0 = *(const LAS u32x2*)(vb + 32 * AV_PITCH + ks * 32), c1 = *(const LAS u32x2*)(vb + 32 * AV_PITCH + ks * 32 + 16);
;                 const bf16x8 v0 = __builtin_bit_cast(bf16x8, ((u32x4){a0.x, a0.y, a1.x, a1.y})), v1 = __builtin_bit_cast(bf16x8, ((u32x4){c0.x, c0.y, c1.x, c1.y}));
;                 oa0 = __builtin_amdgcn_mfma_f32_32x32x16_bf16(v0, pfa, oa0, 0, 0, 0);
;                 oa1 = __builtin_amdgcn_mfma_f32_32x32x16_bf16(v1, pfa, oa1, 0, 0, 0);
;                 ob0 = __builtin_amdgcn_mfma_f32_32x32x16_bf16(v0, pfb, ob0, 0, 0, 0);
;                 ob1 = __builtin_amdgcn_mfma_f32_32x32x16_bf16(v1, pfb, ob1, 0, 0, 0);
;             }
	v_mfma_f32_32x32x16_bf16 v[48:63], v[80:83], v[84:87], v[48:63]
	v_cvt_pk_bf16_f32 v65, v223, v224
	v_cvt_pk_bf16_f32 v66, v225, v226
	v_cvt_pk_bf16_f32 v67, v227, v228
	s_waitcnt lgkmcnt(0)
	v_mfma_f32_32x32x16_bf16 v[32:47], v[88:91], v[84:87], v[32:47]
	v_exp_f32_e32 v84, v68
	v_sub_f32_e32 v68, v72, v204
	v_exp_f32_e32 v229, v68
	v_sub_f32_e32 v68, v73, v204
	v_exp_f32_e32 v230, v68
	ds_read2_b64 v[68:71], v185 offset0:12 offset1:14
	v_sub_f32_e32 v72, v75, v204
	v_mfma_f32_32x32x16_bf16 v[16:31], v[80:83], v[64:67], v[16:31]
	ds_read2_b64 v[80:83], v187 offset0:44 offset1:46
	v_exp_f32_e32 v235, v72
	v_sub_f32_e32 v72, v76, v204
	v_exp_f32_e32 v236, v72
	v_sub_f32_e32 v72, v77, v204
	v_mfma_f32_32x32x16_bf16 v[0:15], v[88:91], v[64:67], v[0:15]
	v_sub_f32_e32 v64, v74, v204
	v_exp_f32_e32 v232, v64
	v_cvt_pk_bf16_f32 v64, v231, v233
	v_cvt_pk_bf16_f32 v65, v238, v239
	v_cvt_pk_bf16_f32 v66, v92, v93
	v_cvt_pk_bf16_f32 v67, v94, v84
	v_exp_f32_e32 v231, v72
	v_sub_f32_e32 v72, v78, v204
	s_waitcnt lgkmcnt(1)
	v_mfma_f32_32x32x16_bf16 v[48:63], v[68:71], v[64:67], v[48:63]
	v_exp_f32_e32 v233, v72
	s_waitcnt lgkmcnt(0)
	v_mfma_f32_32x32x16_bf16 v[32:47], v[80:83], v[64:67], v[32:47]
	v_sub_f32_e32 v64, v79, v204
	v_exp_f32_e32 v234, v64
	v_cvt_pk_bf16_f32 v64, v229, v230
	v_cvt_pk_bf16_f32 v65, v232, v235
	v_cvt_pk_bf16_f32 v66, v236, v231
	v_cvt_pk_bf16_f32 v67, v233, v234
	s_nop 1
	v_mfma_f32_32x32x16_bf16 v[16:31], v[68:71], v[64:67], v[16:31]
	v_add_f32_e32 v68, v238, v237
	v_add_f32_e32 v68, v239, v68
	v_add_f32_e32 v68, v92, v68
	v_add_f32_e32 v68, v93, v68
	v_add_f32_e32 v68, v94, v68
	v_add_f32_e32 v68, v84, v68
	v_add_f32_e32 v198, v198, v68
	v_mfma_f32_32x32x16_bf16 v[0:15], v[80:83], v[64:67], v[0:15]
	s_setprio 1
	ds_read_b128 v[64:67], v199 offset:9216
	ds_read_b128 v[238:241], v199 offset:9248
	s_waitcnt lgkmcnt(1)
	v_mfma_f32_32x32x16_bf16 v[112:127], v[64:67], v[142:145], 0
	v_mfma_f32_32x32x16_bf16 v[96:111], v[64:67], v[146:149], 0
	ds_read_b128 v[64:67], v199 offset:13824
	s_waitcnt lgkmcnt(1)
	v_mfma_f32_32x32x16_bf16 v[112:127], v[238:241], v[154:157], v[112:127]
	v_mfma_f32_32x32x16_bf16 v[96:111], v[238:241], v[162:165], v[96:111]
	ds_read_b128 v[238:241], v199 offset:13856
	s_waitcnt lgkmcnt(1)
	v_mfma_f32_32x32x16_bf16 v[80:95], v[64:67], v[142:145], 0
	v_mfma_f32_32x32x16_bf16 v[64:79], v[64:67], v[146:149], 0
	s_waitcnt lgkmcnt(0)
	v_mfma_f32_32x32x16_bf16 v[80:95], v[238:241], v[154:157], v[80:95]
	v_mfma_f32_32x32x16_bf16 v[64:79], v[238:241], v[162:165], v[64:79]
	ds_read_b128 v[238:241], v199 offset:9280
	s_waitcnt lgkmcnt(0)
	v_mfma_f32_32x32x16_bf16 v[112:127], v[238:241], v[158:161], v[112:127]
	v_mfma_f32_32x32x16_bf16 v[96:111], v[238:241], v[170:173], v[96:111]
	ds_read_b128 v[238:241], v199 offset:13888
	s_waitcnt lgkmcnt(0)
	v_mfma_f32_32x32x16_bf16 v[80:95], v[238:241], v[158:161], v[80:95]
	v_mfma_f32_32x32x16_bf16 v[64:79], v[238:241], v[170:173], v[64:79]
	ds_read_b128 v[238:241], v199 offset:9312
	s_waitcnt lgkmcnt(0)
	v_mfma_f32_32x32x16_bf16 v[112:127], v[238:241], v[166:169], v[112:127]
	v_mfma_f32_32x32x16_bf16 v[96:111], v[238:241], v[174:177], v[96:111]
	ds_read_b128 v[238:241], v199 offset:13920
	s_waitcnt lgkmcnt(0)
	v_mfma_f32_32x32x16_bf16 v[80:95], v[238:241], v[166:169], v[80:95]
	v_mfma_f32_32x32x16_bf16 v[64:79], v[238:241], v[174:177], v[64:79]
	s_setprio 0
	s_nop 9
	v_max_f32_e32 v184, v80, v80
	v_max_f32_e32 v199, v112, v112
	v_max_f32_e32 v184, v199, v184
	v_max3_f32 v199, v81, v114, v82
	v_max3_f32 v184, v184, v113, v115
	v_max3_f32 v199, v199, v116, v84
	v_max3_f32 v184, v184, v83, v117
	v_max3_f32 v199, v199, v118, v86
	v_max3_f32 v184, v184, v85, v119
	v_max3_f32 v199, v199, v120, v88
	v_max3_f32 v184, v184, v87, v121
	v_max3_f32 v199, v199, v122, v90
	v_max3_f32 v184, v184, v89, v123
	v_max3_f32 v199, v199, v124, v92
	v_max3_f32 v184, v184, v91, v125
	v_max3_f32 v199, v199, v126, v94
	v_max3_f32 v184, v184, v93, v127
	v_max3_f32 v184, v184, v95, v199
	ds_bpermute_b32 v199, v181, v184
	s_waitcnt lgkmcnt(0)
	v_max3_f32 v184, v205, v184, v199
	v_add_f32_e32 v199, 0x41000000, v205
	v_cmp_gt_f32_e32 vcc, v184, v199
	s_cbranch_vccz .LBB0_453
	v_sub_f32_e32 v199, v205, v184
	v_exp_f32_e32 v238, v199
	s_nop 0
	v_pk_mul_f32 v[62:63], v[62:63], v[238:239] op_sel_hi:[1,0]
	v_pk_mul_f32 v[60:61], v[60:61], v[238:239] op_sel_hi:[1,0]
	v_pk_mul_f32 v[58:59], v[58:59], v[238:239] op_sel_hi:[1,0]
	v_pk_mul_f32 v[56:57], v[56:57], v[238:239] op_sel_hi:[1,0]
	v_pk_mul_f32 v[54:55], v[54:55], v[238:239] op_sel_hi:[1,0]
	v_pk_mul_f32 v[52:53], v[52:53], v[238:239] op_sel_hi:[1,0]
	v_pk_mul_f32 v[50:51], v[50:51], v[238:239] op_sel_hi:[1,0]
	v_pk_mul_f32 v[48:49], v[48:49], v[238:239] op_sel_hi:[1,0]
	v_pk_mul_f32 v[46:47], v[46:47], v[238:239] op_sel_hi:[1,0]
	v_pk_mul_f32 v[44:45], v[44:45], v[238:239] op_sel_hi:[1,0]
	v_pk_mul_f32 v[42:43], v[42:43], v[238:239] op_sel_hi:[1,0]
	v_pk_mul_f32 v[40:41], v[40:41], v[238:239] op_sel_hi:[1,0]
	v_pk_mul_f32 v[38:39], v[38:39], v[238:239] op_sel_hi:[1,0]
	v_pk_mul_f32 v[36:37], v[36:37], v[238:239] op_sel_hi:[1,0]
	v_pk_mul_f32 v[34:35], v[34:35], v[238:239] op_sel_hi:[1,0]
	v_pk_mul_f32 v[32:33], v[32:33], v[238:239] op_sel_hi:[1,0]
	v_mul_f32_e32 v198, v198, v238
	s_branch .LBB0_454

; template <int DK, bool IS_A>
; __device__ __forceinline__ void attn_unit(const Params& P, int l, LAS unsigned char* lds, int b, int grp, int qtok0, int nkeys) {
;     ...
;             AT_SOFTMAX(pa, ma, la, oa0, oa1);
;             AT_SOFTMAX(pb, mb, lb_, ob0, ob1);
.LBB0_454:
	v_add_f32_e32 v193, 0, v193
	v_add_f32_e32 v193, v206, v193
	v_add_f32_e32 v193, v207, v193
	v_add_f32_e32 v193, v208, v193
	v_add_f32_e32 v193, v209, v193
	v_add_f32_e32 v193, v210, v193
	v_add_f32_e32 v193, v211, v193
	v_add_f32_e32 v193, v212, v193
	v_add_f32_e32 v193, v213, v193
	v_add_f32_e32 v193, v214, v193
	v_add_f32_e32 v193, v215, v193
	v_add_f32_e32 v193, v216, v193
	v_add_f32_e32 v193, v217, v193
	v_add_f32_e32 v193, v218, v193
	v_add_f32_e32 v193, v219, v193
	v_add_f32_e32 v193, v220, v193
	v_add_f32_e32 v193, v221, v193
	v_add_f32_e32 v193, v222, v193
	v_max_f32_e32 v199, v64, v64
	v_max_f32_e32 v205, v96, v96
	v_add_f32_e32 v193, v223, v193
	v_max_f32_e32 v199, v205, v199
	v_add_f32_e32 v193, v224, v193
	v_max3_f32 v205, v65, v98, v66
	v_max3_f32 v199, v199, v97, v99
	v_add_f32_e32 v193, v225, v193
	v_max3_f32 v205, v205, v100, v68
	v_max3_f32 v199, v199, v67, v101
	v_add_f32_e32 v193, v226, v193
	v_max3_f32 v205, v205, v102, v70
	v_max3_f32 v199, v199, v69, v103
	v_add_f32_e32 v193, v227, v193
	v_max3_f32 v205, v205, v104, v72
	v_max3_f32 v199, v199, v71, v105
	v_add_f32_e32 v193, v228, v193
	v_max3_f32 v205, v205, v106, v74
	v_max3_f32 v199, v199, v73, v107
	v_add_f32_e32 v193, v229, v193
	v_max3_f32 v205, v205, v108, v76
	v_max3_f32 v199, v199, v75, v109
	v_add_f32_e32 v193, v230, v193
	v_max3_f32 v205, v205, v110, v78
	v_max3_f32 v199, v199, v77, v111
	v_add_f32_e32 v193, v232, v193
	v_max3_f32 v199, v199, v79, v205
	v_add_f32_e32 v193, v235, v193
	ds_bpermute_b32 v205, v181, v199
	v_add_f32_e32 v193, v236, v193
	v_add_f32_e32 v193, v231, v193
	v_add_f32_e32 v193, v233, v193
	v_add_f32_e32 v193, v234, v193
	v_add_f32_e32 v183, v183, v193
	s_waitcnt lgkmcnt(0)
	v_max3_f32 v193, v204, v199, v205
	v_add_f32_e32 v205, 0x41000000, v204
	v_cmp_gt_f32_e32 vcc, v193, v205
	s_cbranch_vccz .LBB0_456
	v_sub_f32_e32 v199, v204, v193
	v_exp_f32_e32 v204, v199
	s_nop 0
	v_pk_mul_f32 v[30:31], v[30:31], v[204:205] op_sel_hi:[1,0]
	v_pk_mul_f32 v[28:29], v[28:29], v[204:205] op_sel_hi:[1,0]
	v_pk_mul_f32 v[26:27], v[26:27], v[204:205] op_sel_hi:[1,0]
	v_pk_mul_f32 v[24:25], v[24:25], v[204:205] op_sel_hi:[1,0]
	v_pk_mul_f32 v[22:23], v[22:23], v[204:205] op_sel_hi:[1,0]
	v_pk_mul_f32 v[20:21], v[20:21], v[204:205] op_sel_hi:[1,0]
	v_pk_mul_f32 v[18:19], v[18:19], v[204:205] op_sel_hi:[1,0]
	v_pk_mul_f32 v[16:17], v[16:17], v[204:205] op_sel_hi:[1,0]
	v_pk_mul_f32 v[14:15], v[14:15], v[204:205] op_sel_hi:[1,0]
	v_pk_mul_f32 v[12:13], v[12:13], v[204:205] op_sel_hi:[1,0]
	v_pk_mul_f32 v[10:11], v[10:11], v[204:205] op_sel_hi:[1,0]
	v_pk_mul_f32 v[8:9], v[8:9], v[204:205] op_sel_hi:[1,0]
	v_pk_mul_f32 v[6:7], v[6:7], v[204:205] op_sel_hi:[1,0]
	v_pk_mul_f32 v[4:5], v[4:5], v[204:205] op_sel_hi:[1,0]
	v_pk_mul_f32 v[2:3], v[2:3], v[204:205] op_sel_hi:[1,0]
	v_pk_mul_f32 v[0:1], v[0:1], v[204:205] op_sel_hi:[1,0]
	v_mul_f32_e32 v183, v183, v204
	s_branch .LBB0_457
